# nt policy also on EpiRes residual rows, kvconv inputs, weight-transpose tiles and hg_prep token loads
# baseline (speedup 1.0000x reference)
; __device__ __forceinline__ int opaque_tid() { int t = threadIdx.x; asm volatile("" : "+v"(t)); return t; }
; __device__ __forceinline__ void transpose_job(LAS float* tile, const float* src, int ldn, int K, int N, const float* gain, bf16_t* dst, int mode, int noff, int nbatch, size_t sstride, size_t dstride) {
;     const int tid = opaque_tid(); const int tn = N / 64, tk = K / 64, per = tn * tk, total = per * nbatch;
;     int t = blockIdx.x; if (t >= total) return;
;     float v[8];
;     ...
;     TR_LD(t);
.LBB0_78:
	s_lshr_b32 s54, s52, 6
	s_lshr_b32 s10, s9, 6
	s_mul_i32 s55, s54, s10
	v_mov_b32_e32 v26, v200
	s_cmp_ge_i32 s2, s55
	s_cbranch_scc1 .LBB0_49
	v_cvt_f32_u32_e32 v0, s55
	s_sub_i32 s10, 0, s55
	v_cvt_f32_i32_e32 v2, s54
	v_and_b32_e32 v3, 63, v26
	v_rcp_iflag_f32_e32 v0, v0
	v_ashrrev_i32_e32 v30, 6, v26
	v_rcp_iflag_f32_e32 v4, v2
	v_add_u32_e32 v27, 0x200, v26
	v_mul_f32_e32 v0, 0x4f7ffffe, v0
	v_cvt_u32_f32_e32 v0, v0
	v_ashrrev_i32_e32 v31, 6, v27
	v_add_u32_e32 v28, 0x400, v26
	v_ashrrev_i32_e32 v32, 6, v28
	v_readfirstlane_b32 s56, v0
	s_mul_i32 s10, s10, s56
	s_mul_hi_u32 s10, s56, s10
	s_add_i32 s56, s56, s10
	s_mul_hi_u32 s10, s14, s56
	s_mul_i32 s10, s10, s55
	s_sub_i32 s10, s14, s10
	s_sub_i32 s11, s10, s55
	s_cmp_ge_u32 s10, s55
	s_cselect_b32 s10, s11, s10
	s_sub_i32 s11, s10, s55
	s_cmp_ge_u32 s10, s55
	s_cselect_b32 s10, s11, s10
	s_xor_b32 s10, s10, s3
	s_sub_i32 s57, s10, s3
	v_cvt_f32_i32_e32 v5, s57
	v_lshlrev_b32_e32 v0, 2, v3
	s_ashr_i32 s10, s57, 30
	s_or_b32 s58, s10, 1
	v_mul_f32_e32 v3, v5, v4
	v_trunc_f32_e32 v3, v3
	v_fma_f32 v4, -v3, v2, v5
	v_cvt_i32_f32_e32 v3, v3
	v_cmp_ge_f32_e64 s[10:11], |v4|, v2
	s_and_b64 s[10:11], s[10:11], exec
	s_cselect_b32 s10, s58, 0
	v_readfirstlane_b32 s11, v3
	s_add_i32 s10, s11, s10
	s_sext_i32_i16 s11, s10
	s_mul_i32 s10, s10, s54
	s_sub_i32 s10, s57, s10
	s_sext_i32_i16 s10, s10
	s_lshl_b32 s10, s10, 6
	s_lshl_b32 s58, s11, 6
	s_ashr_i32 s11, s10, 31
	s_lshl_b64 s[10:11], s[10:11], 2
	s_add_u32 s10, s0, s10
	v_add_u32_e32 v2, s58, v30
	s_addc_u32 s11, s1, s11
	s_waitcnt vmcnt(10)
	v_lshl_add_u64 v[6:7], s[10:11], 0, v[0:1]
	v_mad_u64_u32 v[4:5], s[10:11], v2, s52, 0
	v_ashrrev_i32_e32 v3, 31, v2
	s_waitcnt vmcnt(9)
	v_mov_b32_e32 v8, v5
	s_waitcnt vmcnt(8)
	v_mad_u64_u32 v[8:9], s[10:11], v3, s52, v[8:9]
	v_mov_b32_e32 v5, v8
	v_lshl_add_u64 v[8:9], v[4:5], 2, v[6:7]
	v_add_u32_e32 v4, s58, v31
	s_waitcnt vmcnt(6)
	v_mad_u64_u32 v[10:11], s[10:11], v4, s52, 0
	v_ashrrev_i32_e32 v5, 31, v4
	s_waitcnt vmcnt(5)
	v_mov_b32_e32 v12, v11
	s_waitcnt vmcnt(4)
	v_mad_u64_u32 v[12:13], s[10:11], v5, s52, v[12:13]
	v_add_u32_e32 v14, s58, v32
	v_mov_b32_e32 v11, v12
	v_mad_u64_u32 v[12:13], s[10:11], v14, s52, 0
	v_ashrrev_i32_e32 v15, 31, v14
	v_mov_b32_e32 v16, v13
	v_add_u32_e32 v29, 0x600, v26
	v_mad_u64_u32 v[16:17], s[10:11], v15, s52, v[16:17]
	v_ashrrev_i32_e32 v33, 6, v29
	v_mov_b32_e32 v13, v16
	v_add_u32_e32 v16, s58, v33
	v_mad_u64_u32 v[18:19], s[10:11], v16, s52, 0
	v_ashrrev_i32_e32 v17, 31, v16
	v_mov_b32_e32 v20, v19
	v_mad_u64_u32 v[20:21], s[10:11], v17, s52, v[20:21]
	v_mov_b32_e32 v19, v20
	v_lshl_add_u64 v[40:41], v[18:19], 2, v[6:7]
	v_add_u32_e32 v18, 0x800, v26
	v_ashrrev_i32_e32 v34, 6, v18
	v_add_u32_e32 v18, s58, v34
	v_mad_u64_u32 v[20:21], s[10:11], v18, s52, 0
	v_ashrrev_i32_e32 v19, 31, v18
	v_mov_b32_e32 v22, v21
	v_mad_u64_u32 v[22:23], s[10:11], v19, s52, v[22:23]
	v_mov_b32_e32 v21, v22
	v_lshl_add_u64 v[42:43], v[20:21], 2, v[6:7]
	v_add_u32_e32 v20, 0xa00, v26
	v_ashrrev_i32_e32 v36, 6, v20
	v_add_u32_e32 v20, s58, v36
	v_mad_u64_u32 v[22:23], s[10:11], v20, s52, 0
	v_ashrrev_i32_e32 v21, 31, v20
	v_mov_b32_e32 v24, v23
	v_mad_u64_u32 v[24:25], s[10:11], v21, s52, v[24:25]
	v_mov_b32_e32 v23, v24
	v_lshl_add_u64 v[44:45], v[22:23], 2, v[6:7]
	v_add_u32_e32 v22, 0xc00, v26
	v_ashrrev_i32_e32 v37, 6, v22
	v_add_u32_e32 v22, s58, v37
	v_mad_u64_u32 v[24:25], s[10:11], v22, s52, 0
	v_ashrrev_i32_e32 v23, 31, v22
	v_mov_b32_e32 v38, v25
	v_mad_u64_u32 v[38:39], s[10:11], v23, s52, v[38:39]
	v_mov_b32_e32 v25, v38
	v_lshl_add_u64 v[46:47], v[24:25], 2, v[6:7]
	v_add_u32_e32 v24, 0xe00, v26
	v_ashrrev_i32_e32 v38, 6, v24
	v_add_u32_e32 v24, s58, v38
	v_mad_u64_u32 v[48:49], s[10:11], v24, s52, 0
	v_ashrrev_i32_e32 v25, 31, v24
	s_waitcnt lgkmcnt(0)
	v_mov_b32_e32 v50, v49
	v_mad_u64_u32 v[50:51], s[10:11], v25, s52, v[50:51]
	v_lshl_add_u64 v[10:11], v[10:11], 2, v[6:7]
	v_lshl_add_u64 v[12:13], v[12:13], 2, v[6:7]
	v_mov_b32_e32 v49, v50
	v_lshl_add_u64 v[48:49], v[48:49], 2, v[6:7]
	global_load_dword v6, v[8:9], off nt
	global_load_dword v7, v[10:11], off nt
	s_nop 0
	global_load_dword v8, v[12:13], off nt
	global_load_dword v9, v[40:41], off nt
	global_load_dword v10, v[42:43], off nt
	global_load_dword v11, v[44:45], off nt
	s_nop 0
	global_load_dword v12, v[46:47], off nt
	global_load_dword v13, v[48:49], off nt
	s_cmp_lg_u64 s[4:5], 0
	s_cselect_b64 s[10:11], -1, 0
	s_cmp_eq_u64 s[4:5], 0
	s_cbranch_scc1 .LBB0_81
	v_lshl_add_u64 v[2:3], v[2:3], 2, s[4:5]
	v_lshl_add_u64 v[4:5], v[4:5], 2, s[4:5]
	v_lshl_add_u64 v[14:15], v[14:15], 2, s[4:5]
	v_lshl_add_u64 v[16:17], v[16:17], 2, s[4:5]
	v_lshl_add_u64 v[18:19], v[18:19], 2, s[4:5]
	v_lshl_add_u64 v[20:21], v[20:21], 2, s[4:5]
	v_lshl_add_u64 v[22:23], v[22:23], 2, s[4:5]
	v_lshl_add_u64 v[24:25], v[24:25], 2, s[4:5]
	global_load_dword v2, v[2:3], off
	s_nop 0
	global_load_dword v3, v[4:5], off
	s_nop 0
	global_load_dword v4, v[14:15], off
	global_load_dword v5, v[16:17], off
	s_nop 0
	global_load_dword v14, v[18:19], off
	global_load_dword v15, v[20:21], off
	global_load_dword v16, v[22:23], off
	global_load_dword v17, v[24:25], off
	s_waitcnt vmcnt(6)
	v_pk_mul_f32 v[6:7], v[6:7], v[2:3]
	s_waitcnt vmcnt(4)
	v_pk_mul_f32 v[8:9], v[8:9], v[4:5]
	s_waitcnt vmcnt(2)
	v_pk_mul_f32 v[10:11], v[10:11], v[14:15]
	s_waitcnt vmcnt(0)
	v_pk_mul_f32 v[12:13], v[12:13], v[16:17]

; __device__ __forceinline__ void transpose_job(LAS float* tile, const float* src, int ldn, int K, int N, const float* gain, bf16_t* dst, int mode, int noff, int nbatch, size_t sstride, size_t dstride) {
;     ...
;     for (; t < total; t += gridDim.x) {
;         const int bb = t / per, tt = t % per; const int k0 = (tt / tn) * 64, n0 = (tt % tn) * 64; bf16_t* d = dst + (size_t)bb * dstride;
; #pragma unroll
;         for (int i = 0; i < 8; ++i) { const int idx = tid + i * 512, kk = idx >> 6, nn = idx & 63; tile[kk * 65 + nn] = v[i]; }
;         __syncthreads();
;         if (t + (int)gridDim.x < total) TR_LD(t + (int)gridDim.x);
.LBB0_83:
	s_add_i32 s58, s0, s34
	s_cmp_ge_i32 s58, s55
	s_cselect_b64 s[38:39], -1, 0
	s_and_b64 vcc, exec, s[38:39]
	s_waitcnt vmcnt(7)
	ds_write_b32 v0, v6
	s_waitcnt vmcnt(6)
	ds_write_b32 v47, v7
	s_waitcnt vmcnt(5)
	ds_write_b32 v48, v8
	s_waitcnt vmcnt(4)
	ds_write_b32 v49, v9
	s_waitcnt vmcnt(3)
	ds_write_b32 v50, v10
	s_waitcnt vmcnt(2)
	ds_write_b32 v51, v11
	s_waitcnt vmcnt(1)
	ds_write_b32 v52, v12
	s_waitcnt vmcnt(0)
	ds_write_b32 v53, v13
	s_waitcnt lgkmcnt(0)
	s_barrier
	s_cbranch_vccnz .LBB0_86
	s_abs_i32 s59, s58
	s_mul_hi_u32 s60, s59, s56
	s_mul_i32 s60, s60, s55
	s_sub_i32 s59, s59, s60
	s_ashr_i32 s1, s58, 31
	s_sub_i32 s60, s59, s55
	s_cmp_ge_u32 s59, s55
	s_cselect_b32 s59, s60, s59
	s_sub_i32 s60, s59, s55
	s_cmp_ge_u32 s59, s55
	s_cselect_b32 s59, s60, s59
	s_xor_b32 s59, s59, s1
	s_sub_i32 s1, s59, s1
	s_abs_i32 s60, s1
	s_mul_hi_u32 s61, s60, s57
	s_mul_i32 s62, s61, s54
	s_sub_i32 s60, s60, s62
	s_ashr_i32 s59, s1, 31
	s_add_i32 s62, s61, 1
	s_sub_i32 s63, s60, s54
	s_cmp_ge_u32 s60, s54
	s_cselect_b32 s61, s62, s61
	s_cselect_b32 s60, s63, s60
	s_add_i32 s62, s61, 1
	s_cmp_ge_u32 s60, s54
	s_cselect_b32 s60, s62, s61
	s_xor_b32 s60, s60, s59
	s_sub_i32 s59, s60, s59
	s_lshl_b32 s62, s59, 6
	s_mul_i32 s59, s59, s54
	s_sub_i32 s1, s1, s59
	s_lshl_b32 s60, s1, 6
	s_ashr_i32 s61, s60, 31
	v_add_u32_e32 v14, s62, v30
	v_lshl_add_u64 v[6:7], s[60:61], 2, v[2:3]
	v_mad_u64_u32 v[8:9], s[60:61], v14, s52, 0
	v_ashrrev_i32_e32 v15, 31, v14
	v_mov_b32_e32 v10, v9
	v_mad_u64_u32 v[10:11], s[60:61], v15, s52, v[10:11]
	v_add_u32_e32 v16, s62, v31
	v_mov_b32_e32 v9, v10
	v_mad_u64_u32 v[10:11], s[60:61], v16, s52, 0
	v_ashrrev_i32_e32 v17, 31, v16
	v_mov_b32_e32 v12, v11
	v_mad_u64_u32 v[12:13], s[60:61], v17, s52, v[12:13]
	v_add_u32_e32 v18, s62, v32
	v_mov_b32_e32 v11, v12
	v_mad_u64_u32 v[12:13], s[60:61], v18, s52, 0
	v_ashrrev_i32_e32 v19, 31, v18
	v_mov_b32_e32 v20, v13
	v_mad_u64_u32 v[20:21], s[60:61], v19, s52, v[20:21]
	v_mov_b32_e32 v13, v20
	v_add_u32_e32 v20, s62, v33
	v_mad_u64_u32 v[22:23], s[60:61], v20, s52, 0
	v_ashrrev_i32_e32 v21, 31, v20
	v_mov_b32_e32 v24, v23
	v_mad_u64_u32 v[24:25], s[60:61], v21, s52, v[24:25]
	v_mov_b32_e32 v23, v24
	v_lshl_add_u64 v[54:55], v[22:23], 2, v[6:7]
	v_add_u32_e32 v22, s62, v34
	v_mad_u64_u32 v[24:25], s[60:61], v22, s52, 0
	v_ashrrev_i32_e32 v23, 31, v22
	v_mov_b32_e32 v26, v25
	v_mad_u64_u32 v[26:27], s[60:61], v23, s52, v[26:27]
	v_mov_b32_e32 v25, v26
	v_lshl_add_u64 v[56:57], v[24:25], 2, v[6:7]
	v_add_u32_e32 v24, s62, v36
	v_mad_u64_u32 v[26:27], s[60:61], v24, s52, 0
	v_ashrrev_i32_e32 v25, 31, v24
	v_mov_b32_e32 v28, v27
	v_mad_u64_u32 v[28:29], s[60:61], v25, s52, v[28:29]
	v_mov_b32_e32 v27, v28
	v_lshl_add_u64 v[58:59], v[26:27], 2, v[6:7]
	v_add_u32_e32 v26, s62, v37
	v_mad_u64_u32 v[28:29], s[60:61], v26, s52, 0
	v_ashrrev_i32_e32 v27, 31, v26
	v_mov_b32_e32 v60, v29
	v_mad_u64_u32 v[60:61], s[60:61], v27, s52, v[60:61]
	v_mov_b32_e32 v29, v60
	v_lshl_add_u64 v[60:61], v[28:29], 2, v[6:7]
	v_add_u32_e32 v28, s62, v38
	v_mad_u64_u32 v[62:63], s[60:61], v28, s52, 0
	v_ashrrev_i32_e32 v29, 31, v28
	v_mov_b32_e32 v64, v63
	v_mad_u64_u32 v[64:65], s[60:61], v29, s52, v[64:65]
	v_lshl_add_u64 v[8:9], v[8:9], 2, v[6:7]
	v_lshl_add_u64 v[10:11], v[10:11], 2, v[6:7]
	v_lshl_add_u64 v[12:13], v[12:13], 2, v[6:7]
	v_mov_b32_e32 v63, v64
	v_lshl_add_u64 v[62:63], v[62:63], 2, v[6:7]
	global_load_dword v6, v[8:9], off nt
	global_load_dword v7, v[10:11], off nt
	s_nop 0
	global_load_dword v8, v[12:13], off nt
	global_load_dword v9, v[54:55], off nt
	global_load_dword v10, v[56:57], off nt
	global_load_dword v11, v[58:59], off nt
	s_nop 0
	global_load_dword v12, v[60:61], off nt
	global_load_dword v13, v[62:63], off nt
	s_andn2_b64 vcc, exec, s[10:11]
	s_cbranch_vccnz .LBB0_86
	v_lshl_add_u64 v[14:15], v[14:15], 2, s[4:5]
	v_lshl_add_u64 v[16:17], v[16:17], 2, s[4:5]
	v_lshl_add_u64 v[18:19], v[18:19], 2, s[4:5]
	v_lshl_add_u64 v[20:21], v[20:21], 2, s[4:5]
	v_lshl_add_u64 v[22:23], v[22:23], 2, s[4:5]
	v_lshl_add_u64 v[24:25], v[24:25], 2, s[4:5]
	v_lshl_add_u64 v[26:27], v[26:27], 2, s[4:5]
	v_lshl_add_u64 v[28:29], v[28:29], 2, s[4:5]
	global_load_dword v14, v[14:15], off
	s_nop 0
	global_load_dword v15, v[16:17], off
	s_nop 0
	global_load_dword v16, v[18:19], off
	global_load_dword v17, v[20:21], off
	s_nop 0
	global_load_dword v18, v[22:23], off
	global_load_dword v19, v[24:25], off
	global_load_dword v20, v[26:27], off
	global_load_dword v21, v[28:29], off
	s_waitcnt vmcnt(6)
	v_pk_mul_f32 v[6:7], v[6:7], v[14:15]
	s_waitcnt vmcnt(4)
	v_pk_mul_f32 v[8:9], v[8:9], v[16:17]
	s_waitcnt vmcnt(2)
	v_pk_mul_f32 v[10:11], v[10:11], v[18:19]
	s_waitcnt vmcnt(0)
	v_pk_mul_f32 v[12:13], v[12:13], v[20:21]

; __device__ __forceinline__ unsigned cvt_pk_bf16(float lo, float hi) { f32x2 f = {lo, hi}; bf16x2_t v = __builtin_convertvector(f, bf16x2_t); return __builtin_bit_cast(unsigned, v); }
; __device__ __forceinline__ void ph_kvconv(const Params& p, LAS unsigned char* lds) {
;     ...
;         const size_t nvec = 24 * per / 4, stride = (size_t)gridDim.x * 512;
;         for (size_t i0 = (size_t)blockIdx.x * 512 + tid; i0 < nvec; i0 += 4 * stride) {
;             f32x4 v[4];
; #pragma unroll
;             for (int j = 0; j < 4; ++j) { const size_t i = i0 + j * stride; if (i < nvec) { const size_t e = i * 4; const int b = (int)(e / per); const size_t off = e % per;
;                 const float* src = b < 8 ? p.out + O_PMK + (size_t)b * per + off : p.in[3] + (size_t)(b - 8) * per + off; v[j] = *(const f32x4*)src; } }
; #pragma unroll
;             for (int j = 0; j < 4; ++j) { const size_t i = i0 + j * stride; if (i < nvec) { u32x2 w; w.x = cvt_pk_bf16(v[j][0], v[j][1]); w.y = cvt_pk_bf16(v[j][2], v[j][3]); *(u32x2*)(kb + i * 4) = w; } }
;         }
.LBB0_326:
	v_lshrrev_b64 v[2:3], 16, v[44:45]
	v_cmp_lt_u64_e32 vcc, s[72:73], v[44:45]
	s_and_saveexec_b64 s[0:1], vcc
	s_xor_b64 s[0:1], exec, s[0:1]
	v_lshlrev_b64 v[0:1], 18, v[2:3]
	v_lshl_add_u64 v[0:1], v[0:1], 0, s[74:75]
	v_and_b32_e32 v1, 0x3ffff, v1
	v_lshl_add_u64 v[0:1], v[0:1], 2, s[42:43]
	s_andn2_saveexec_b64 s[0:1], s[0:1]
	v_lshlrev_b64 v[0:1], 20, v[2:3]
	v_lshl_add_u64 v[0:1], s[38:39], 0, v[0:1]
	s_or_b64 exec, exec, s[0:1]
	v_and_b32_e32 v2, 0x3fffc, v34
	v_lshlrev_b32_e32 v42, 2, v2
	v_lshl_add_u64 v[0:1], v[0:1], 0, v[42:43]
	global_load_dwordx4 v[0:3], v[0:1], off nt
	v_lshl_add_u64 v[46:47], v[44:45], 0, s[30:31]
	v_cmp_gt_u64_e32 vcc, s[8:9], v[46:47]
	s_and_saveexec_b64 s[4:5], vcc
	s_cbranch_execz .LBB0_336
	v_lshrrev_b64 v[6:7], 16, v[46:47]
	v_cmp_lt_u64_e64 s[0:1], s[72:73], v[46:47]
	s_and_saveexec_b64 s[6:7], s[0:1]
	s_xor_b64 s[0:1], exec, s[6:7]
	v_lshlrev_b64 v[4:5], 18, v[6:7]
	v_lshl_add_u64 v[4:5], v[4:5], 0, s[74:75]
	v_and_b32_e32 v5, 0x3ffff, v5
	v_lshl_add_u64 v[4:5], v[4:5], 2, s[42:43]
	s_andn2_saveexec_b64 s[0:1], s[0:1]
	v_lshlrev_b64 v[4:5], 20, v[6:7]
	v_lshl_add_u64 v[4:5], s[38:39], 0, v[4:5]
	s_or_b64 exec, exec, s[0:1]
	v_add_u32_e32 v6, s68, v34
	v_and_b32_e32 v6, 0x3fffc, v6
	v_lshlrev_b32_e32 v42, 2, v6
	v_lshl_add_u64 v[4:5], v[4:5], 0, v[42:43]
	global_load_dwordx4 v[4:7], v[4:5], off nt
.LBB0_336:
	s_or_b64 exec, exec, s[4:5]
	v_lshl_add_u64 v[48:49], s[54:55], 0, v[44:45]
	s_waitcnt vmcnt(0)
	v_mov_b64_e32 v[30:31], v[14:15]
	v_cmp_gt_u64_e64 s[0:1], s[8:9], v[48:49]
	v_mov_b64_e32 v[28:29], v[12:13]
	v_mov_b64_e32 v[26:27], v[10:11]
	v_mov_b64_e32 v[24:25], v[8:9]
	v_mov_b64_e32 v[22:23], v[6:7]
	v_mov_b64_e32 v[20:21], v[4:5]
	v_mov_b64_e32 v[18:19], v[2:3]
	v_mov_b64_e32 v[16:17], v[0:1]
	s_and_saveexec_b64 s[6:7], s[0:1]
	s_cbranch_execz .LBB0_342
	v_lshrrev_b64 v[10:11], 16, v[48:49]
	v_cmp_lt_u64_e64 s[4:5], s[72:73], v[48:49]
	s_and_saveexec_b64 s[52:53], s[4:5]
	s_xor_b64 s[4:5], exec, s[52:53]
	v_lshlrev_b64 v[8:9], 18, v[10:11]
	v_lshl_add_u64 v[8:9], v[8:9], 0, s[74:75]
	v_and_b32_e32 v9, 0x3ffff, v9
	v_lshl_add_u64 v[8:9], v[8:9], 2, s[42:43]
	s_andn2_saveexec_b64 s[4:5], s[4:5]
	v_lshlrev_b64 v[8:9], 20, v[10:11]
	v_lshl_add_u64 v[8:9], s[38:39], 0, v[8:9]
	s_or_b64 exec, exec, s[4:5]
	v_add_u32_e32 v10, s56, v34
	v_and_b32_e32 v10, 0x3fffc, v10
	v_lshlrev_b32_e32 v42, 2, v10
	v_lshl_add_u64 v[8:9], v[8:9], 0, v[42:43]
	global_load_dwordx4 v[8:11], v[8:9], off nt
	s_waitcnt vmcnt(0)
	v_mov_b64_e32 v[30:31], v[14:15]
	v_mov_b64_e32 v[28:29], v[12:13]
	v_mov_b64_e32 v[22:23], v[6:7]
	v_mov_b64_e32 v[20:21], v[4:5]
	v_mov_b64_e32 v[18:19], v[2:3]
	v_mov_b64_e32 v[16:17], v[0:1]
	v_mov_b64_e32 v[26:27], v[10:11]
	v_mov_b64_e32 v[24:25], v[8:9]
.LBB0_342:
	s_or_b64 exec, exec, s[6:7]
	v_lshl_add_u64 v[44:45], s[64:65], 0, v[44:45]
	v_cmp_gt_u64_e64 s[4:5], s[8:9], v[44:45]
	s_and_saveexec_b64 s[78:79], s[4:5]
	s_cbranch_execz .LBB0_348
	v_lshrrev_b64 v[16:17], 16, v[44:45]
	v_cmp_lt_u64_e64 s[6:7], s[72:73], v[44:45]
	s_and_saveexec_b64 s[52:53], s[6:7]
	s_xor_b64 s[6:7], exec, s[52:53]
	v_lshlrev_b64 v[12:13], 18, v[16:17]
	v_lshl_add_u64 v[12:13], v[12:13], 0, s[74:75]
	v_and_b32_e32 v13, 0x3ffff, v13
	v_lshl_add_u64 v[12:13], v[12:13], 2, s[42:43]
	s_andn2_saveexec_b64 s[6:7], s[6:7]
	v_lshlrev_b64 v[12:13], 20, v[16:17]
	v_lshl_add_u64 v[12:13], s[38:39], 0, v[12:13]
	s_or_b64 exec, exec, s[6:7]
	v_add_u32_e32 v14, s3, v34
	v_and_b32_e32 v14, 0x3fffc, v14
	v_lshlrev_b32_e32 v42, 2, v14
	v_lshl_add_u64 v[12:13], v[12:13], 0, v[42:43]
	global_load_dwordx4 v[48:51], v[12:13], off nt
	s_waitcnt vmcnt(0)
	v_mov_b32_e32 v14, v50
	v_mov_b32_e32 v12, v48
	v_mov_b32_e32 v13, v49
	v_mov_b64_e32 v[30:31], v[14:15]
	v_mov_b64_e32 v[28:29], v[12:13]
	v_mov_b64_e32 v[26:27], v[10:11]
	v_mov_b64_e32 v[24:25], v[8:9]
	v_mov_b64_e32 v[22:23], v[6:7]
	v_mov_b64_e32 v[20:21], v[4:5]
	v_mov_b64_e32 v[18:19], v[2:3]
	v_mov_b64_e32 v[16:17], v[0:1]
	v_mov_b32_e32 v15, v51
	v_mov_b32_e32 v31, v51

; #define LAS __attribute__((address_space(3)))
; __device__ __forceinline__ int opaque_tid() { int t = threadIdx.x; asm volatile("" : "+v"(t)); return t; }
; __device__ __forceinline__ void transpose_job(LAS float* tile, const float* src, int ldn, int K, int N, const float* gain, bf16_t* dst, int mode, int noff, int nbatch, size_t sstride, size_t dstride) {
;     const int tid = opaque_tid(); const int tn = N / 64, tk = K / 64, per = tn * tk, total = per * nbatch;
;     int t = blockIdx.x; if (t >= total) return;
;     float v[8];
;     ...
;     TR_LD(t);
; __device__ __forceinline__ void ph_kvconv(const Params& p, LAS unsigned char* lds) {
;     ...
;     LAS float* tile = (LAS float*)lds;
; #pragma unroll 1
;     for (int job = 0; job < 2; ++job) {
;         const float* src = job ? p.in[4] : p.out + O_PMV; bf16_t* dst = job ? vt + 8 * per : vt; const int nb = job ? 16 : 8;
;         transpose_job(tile, src, 1024, 256, 1024, nullptr, dst, 0, 0, nb, per, per);
.LBB0_356:
	s_and_b64 s[8:9], s[6:7], exec
	s_cselect_b32 s19, s15, 0x400
	v_mov_b32_e32 v2, v200
	s_cmp_ge_i32 s2, s19
	s_cbranch_scc1 .LBB0_355
	s_and_b64 s[8:9], s[6:7], exec
	s_cselect_b32 s8, s17, 0x1ac80000
	s_cselect_b32 s30, s11, s45
	s_cselect_b32 s31, s10, s44
	s_add_u32 s33, s92, s8
	s_addc_u32 s35, s93, 0
	s_add_u32 s8, s31, s0
	s_addc_u32 s9, s30, s1
	v_ashrrev_i32_e32 v4, 6, v2
	v_and_b32_e32 v36, 63, v2
	s_add_u32 s8, s8, s4
	v_add_u32_e32 v6, s3, v4
	s_addc_u32 s9, s9, s5
	v_lshlrev_b32_e32 v0, 2, v36
	s_waitcnt vmcnt(10)
	v_ashrrev_i32_e32 v7, 31, v6
	v_add_u32_e32 v35, 0x200, v2
	s_waitcnt vmcnt(4)
	v_lshl_add_u64 v[12:13], s[8:9], 0, v[0:1]
	v_lshlrev_b64 v[6:7], 12, v[6:7]
	v_ashrrev_i32_e32 v5, 6, v35
	v_lshl_add_u64 v[14:15], v[12:13], 0, v[6:7]
	v_add_u32_e32 v6, s3, v5
	v_ashrrev_i32_e32 v7, 31, v6
	v_lshlrev_b64 v[6:7], 12, v[6:7]
	v_add_u32_e32 v37, 0x400, v2
	v_lshl_add_u64 v[16:17], v[12:13], 0, v[6:7]
	v_ashrrev_i32_e32 v6, 6, v37
	v_add_u32_e32 v8, s3, v6
	v_ashrrev_i32_e32 v9, 31, v8
	v_add_u32_e32 v38, 0x600, v2
	v_lshlrev_b64 v[8:9], 12, v[8:9]
	v_ashrrev_i32_e32 v7, 6, v38
	v_lshl_add_u64 v[18:19], v[12:13], 0, v[8:9]
	v_add_u32_e32 v8, s3, v7
	v_ashrrev_i32_e32 v9, 31, v8
	v_lshlrev_b64 v[8:9], 12, v[8:9]
	v_add_u32_e32 v3, 0x800, v2
	v_lshl_add_u64 v[20:21], v[12:13], 0, v[8:9]
	v_ashrrev_i32_e32 v8, 6, v3
	v_add_u32_e32 v10, s3, v8
	v_ashrrev_i32_e32 v11, 31, v10
	v_add_u32_e32 v3, 0xa00, v2
	v_lshlrev_b64 v[10:11], 12, v[10:11]
	v_ashrrev_i32_e32 v9, 6, v3
	v_lshl_add_u64 v[22:23], v[12:13], 0, v[10:11]
	v_add_u32_e32 v10, s3, v9
	v_ashrrev_i32_e32 v11, 31, v10
	v_lshlrev_b64 v[10:11], 12, v[10:11]
	v_add_u32_e32 v3, 0xc00, v2
	v_lshl_add_u64 v[24:25], v[12:13], 0, v[10:11]
	v_ashrrev_i32_e32 v10, 6, v3
	v_add_u32_e32 v3, 0xe00, v2
	v_ashrrev_i32_e32 v11, 6, v3
	v_add_u32_e32 v26, s3, v10
	v_add_u32_e32 v28, s3, v11
	v_ashrrev_i32_e32 v27, 31, v26
	v_ashrrev_i32_e32 v29, 31, v28
	v_lshlrev_b64 v[26:27], 12, v[26:27]
	v_lshlrev_b64 v[28:29], 12, v[28:29]
	v_lshl_add_u64 v[26:27], v[12:13], 0, v[26:27]
	v_lshl_add_u64 v[12:13], v[12:13], 0, v[28:29]
	global_load_dword v3, v[14:15], off nt
	global_load_dword v28, v[16:17], off nt
	global_load_dword v29, v[18:19], off nt
	global_load_dword v30, v[20:21], off nt
	global_load_dword v31, v[22:23], off nt
	global_load_dword v32, v[24:25], off nt
	global_load_dword v33, v[26:27], off nt
	global_load_dword v34, v[12:13], off nt
	v_add_u32_e32 v27, 0, v0
	v_lshlrev_b32_e32 v0, 1, v2
	v_and_b32_e32 v0, 62, v0
	v_mad_u32_u24 v19, v0, s18, 0
	v_mul_lo_u32 v20, v4, s18
	v_mul_lo_u32 v21, v5, s18
	v_mul_lo_u32 v22, v6, s18
	v_mul_lo_u32 v23, v7, s18
	v_mul_lo_u32 v24, v8, s18
	v_mul_lo_u32 v25, v9, s18
	v_mul_lo_u32 v26, v10, s18
	v_mul_lo_u32 v39, v11, s18
	v_ashrrev_i32_e32 v12, 5, v2
	v_ashrrev_i32_e32 v14, 5, v35
	v_ashrrev_i32_e32 v16, 5, v37
	v_ashrrev_i32_e32 v18, 5, v38
	v_lshl_add_u32 v13, v12, 2, v19
	v_lshl_add_u32 v15, v14, 2, v19
	v_lshl_add_u32 v17, v16, 2, v19
	v_lshl_add_u32 v19, v18, 2, v19
	v_add_u32_e32 v20, v27, v20
	v_add_u32_e32 v21, v27, v21
	v_add_u32_e32 v22, v27, v22
	v_add_u32_e32 v23, v27, v23
	v_add_u32_e32 v24, v27, v24
	v_add_u32_e32 v25, v27, v25
	v_add_u32_e32 v26, v27, v26
	v_add_u32_e32 v27, v27, v39
	v_lshlrev_b32_e32 v2, 2, v36
	v_lshlrev_b32_e32 v0, 1, v0
	s_mov_b32 s39, s2
	s_branch .LBB0_359

; __device__ __forceinline__ void transpose_job(LAS float* tile, const float* src, int ldn, int K, int N, const float* gain, bf16_t* dst, int mode, int noff, int nbatch, size_t sstride, size_t dstride) {
;     ...
;     for (; t < total; t += gridDim.x) {
;         const int bb = t / per, tt = t % per; const int k0 = (tt / tn) * 64, n0 = (tt % tn) * 64; bf16_t* d = dst + (size_t)bb * dstride;
; #pragma unroll
;         for (int i = 0; i < 8; ++i) { const int idx = tid + i * 512, kk = idx >> 6, nn = idx & 63; tile[kk * 65 + nn] = v[i]; }
;         __syncthreads();
;         if (t + (int)gridDim.x < total) TR_LD(t + (int)gridDim.x);
.LBB0_359:
	s_add_i32 s38, s39, s34
	s_cmp_ge_i32 s38, s19
	s_cselect_b64 s[8:9], -1, 0
	s_and_b64 vcc, exec, s[8:9]
	s_waitcnt vmcnt(7)
	ds_write_b32 v20, v3
	s_waitcnt vmcnt(6)
	ds_write_b32 v21, v28
	s_waitcnt vmcnt(5)
	ds_write_b32 v22, v29
	s_waitcnt vmcnt(4)
	ds_write_b32 v23, v30
	s_waitcnt vmcnt(3)
	ds_write_b32 v24, v31
	s_waitcnt vmcnt(2)
	ds_write_b32 v25, v32
	s_waitcnt vmcnt(1)
	ds_write_b32 v26, v33
	s_waitcnt vmcnt(0)
	ds_write_b32 v27, v34
	s_waitcnt lgkmcnt(0)
	s_barrier
	s_cbranch_vccnz .LBB0_358
	s_ashr_i32 s42, s38, 31
	s_lshr_b32 s42, s42, 26
	s_add_i32 s43, s38, s42
	s_ashr_i32 s42, s43, 6
	s_and_b32 s43, s43, 0xffc0
	s_sub_i32 s43, s38, s43
	s_bfe_i32 s50, s43, 0x80000
	s_bfe_u32 s50, s50, 0x4000b
	s_add_i32 s50, s43, s50
	s_bfe_i32 s51, s50, 0x80000
	s_and_b32 s50, s50, 0xf0
	s_sub_i32 s43, s43, s50
	s_sext_i32_i16 s51, s51
	s_sext_i32_i8 s43, s43
	s_lshl_b32 s51, s51, 2
	s_lshl_b32 s50, s43, 6
	s_ashr_i32 s43, s42, 31
	s_and_b32 s52, s51, 0xffffffc0
	s_lshl_b64 s[42:43], s[42:43], 20
	s_add_u32 s53, s31, s42
	s_addc_u32 s54, s30, s43
	s_ashr_i32 s51, s50, 31
	s_lshl_b64 s[42:43], s[50:51], 2
	s_add_u32 s42, s53, s42
	v_add_u32_e32 v30, s52, v4
	v_add_u32_e32 v32, s52, v5
	v_add_u32_e32 v34, s52, v6
	s_addc_u32 s43, s54, s43
	v_mov_b32_e32 v3, v1
	v_ashrrev_i32_e32 v31, 31, v30
	v_ashrrev_i32_e32 v33, 31, v32
	v_ashrrev_i32_e32 v35, 31, v34
	v_add_u32_e32 v36, s52, v7
	v_add_u32_e32 v38, s52, v8
	v_add_u32_e32 v40, s52, v9
	v_add_u32_e32 v42, s52, v10
	v_add_u32_e32 v44, s52, v11
	v_lshl_add_u64 v[28:29], s[42:43], 0, v[2:3]
	v_lshlrev_b64 v[30:31], 12, v[30:31]
	v_lshlrev_b64 v[32:33], 12, v[32:33]
	v_lshlrev_b64 v[34:35], 12, v[34:35]
	v_ashrrev_i32_e32 v37, 31, v36
	v_ashrrev_i32_e32 v39, 31, v38
	v_ashrrev_i32_e32 v41, 31, v40
	v_ashrrev_i32_e32 v43, 31, v42
	v_ashrrev_i32_e32 v45, 31, v44
	v_lshl_add_u64 v[30:31], v[28:29], 0, v[30:31]
	v_lshl_add_u64 v[32:33], v[28:29], 0, v[32:33]
	v_lshl_add_u64 v[34:35], v[28:29], 0, v[34:35]
	v_lshlrev_b64 v[36:37], 12, v[36:37]
	v_lshlrev_b64 v[38:39], 12, v[38:39]
	v_lshlrev_b64 v[40:41], 12, v[40:41]
	v_lshlrev_b64 v[42:43], 12, v[42:43]
	v_lshlrev_b64 v[44:45], 12, v[44:45]
	v_lshl_add_u64 v[36:37], v[28:29], 0, v[36:37]
	v_lshl_add_u64 v[38:39], v[28:29], 0, v[38:39]
	v_lshl_add_u64 v[40:41], v[28:29], 0, v[40:41]
	v_lshl_add_u64 v[42:43], v[28:29], 0, v[42:43]
	v_lshl_add_u64 v[44:45], v[28:29], 0, v[44:45]
	global_load_dword v3, v[30:31], off nt
	global_load_dword v28, v[32:33], off nt
	global_load_dword v29, v[34:35], off nt
	s_nop 0
	global_load_dword v30, v[36:37], off nt
	global_load_dword v31, v[38:39], off nt
	global_load_dword v32, v[40:41], off nt
	global_load_dword v33, v[42:43], off nt
	global_load_dword v34, v[44:45], off nt
	s_branch .LBB0_358

; __device__ __forceinline__ float bf1(bf16_t b) { return __uint_as_float(((unsigned)b) << 16); }
; __device__ __forceinline__ float sigmoidf_(float x) { return __builtin_amdgcn_rcpf(1.0f + __expf(-x)); }
; __device__ __forceinline__ void hg_prep_chunk(const Params& p, LAS unsigned char* lds, int task) {
;     ...
;     if (task < 2048) { const int seq = task >> 6, ch = task & 63; h = seq & 3; row0 = (seq >> 2) * 4096 + ch * 64; TC = 64; }
;     else { const int s = task - 2048; h = s & 3; row0 = NTOKP + (s >> 2) * 32; TC = 32; }
;     const int c = tid & 127, sg = tid >> 7;
;     const float l0 = p.in[8][h * 128 + c], l1 = p.in[8][512 + h * 128 + c]; const float lb = 1.0f / (1.0f + __expf(l1 - l0)), omlb = 1.0f - lb;
;     const bool valid = sg * 16 < TC;
;     float cp[16], kx[16], qv[16], vv[16]; float run = 1.f;
;     {
;         const bf16_t* rp = phg + (size_t)(row0 + (valid ? sg * 16 : 0)) * HGC + h * 128 + c; bf16_t rq[16], rf[16], rv[16];
; #pragma unroll
;         for (int j = 0; j < 16; ++j) { rq[j] = rp[(size_t)j * HGC]; rf[j] = rp[(size_t)j * HGC + 512]; rv[j] = rp[(size_t)j * HGC + 1024]; }
; #pragma unroll
;         for (int j = 0; j < 16; ++j) {
;             const float sgm = sigmoidf_(bf1(rf[j])); const float f = valid ? lb + omlb * sgm : 1.0f; run *= f; cp[j] = run;
;             kx[j] = valid ? omlb * (1.0f - sgm) : 0.f; qv[j] = valid ? bf1(rq[j]) : 0.f; vv[j] = valid ? bf1(rv[j]) : 0.f;
;         }
;     }
.LBB0_368:
	s_and_b32 s71, s4, 3
	v_and_b32_e32 v9, 0x7f, v8
	v_ashrrev_i32_e32 v11, 7, v8
	s_lshl_b32 s53, s71, 7
	v_or_b32_e32 v0, s53, v9
	v_readlane_b32 s72, v236, 7
	v_lshlrev_b32_e32 v10, 4, v11
	v_lshlrev_b32_e32 v0, 2, v0
	v_readlane_b32 s73, v236, 8
	v_cmp_gt_i32_e64 s[4:5], s69, v10
	s_nop 3
	global_load_dword v33, v0, s[72:73]
	global_load_dword v51, v0, s[72:73] offset:2048
	v_cndmask_b32_e64 v0, 0, v10, s[4:5]
	v_add_u32_e32 v0, s70, v0
	v_ashrrev_i32_e32 v1, 31, v0
	v_lshlrev_b64 v[0:1], 12, v[0:1]
	v_lshl_add_u64 v[0:1], s[0:1], 0, v[0:1]
	s_lshl_b32 s8, s71, 8
	v_lshl_add_u64 v[0:1], v[0:1], 0, s[8:9]
	v_lshlrev_b32_e32 v12, 1, v9
	v_lshl_add_u64 v[0:1], v[0:1], 0, v[12:13]
	v_add_co_u32_e32 v2, vcc, s38, v0
	global_load_ushort v52, v[0:1], off offset:1024 nt
	s_nop 0
	v_addc_co_u32_e32 v3, vcc, 0, v1, vcc
	v_add_co_u32_e32 v4, vcc, s39, v0
	v_mov_b32_e32 v71, 0
	s_nop 0
	v_addc_co_u32_e32 v5, vcc, 0, v1, vcc
	v_add_co_u32_e32 v16, vcc, s42, v0
	v_readlane_b32 s74, v236, 9
	s_nop 0
	v_addc_co_u32_e32 v17, vcc, 0, v1, vcc
	v_add_co_u32_e32 v14, vcc, s35, v0
	v_readlane_b32 s75, v236, 10
	s_nop 0
	v_addc_co_u32_e32 v15, vcc, 0, v1, vcc
	v_add_co_u32_e32 v20, vcc, s43, v0
	v_readlane_b32 s76, v236, 11
	s_nop 0
	v_addc_co_u32_e32 v21, vcc, 0, v1, vcc
	v_add_co_u32_e32 v22, vcc, s44, v0
	v_readlane_b32 s77, v236, 12
	s_nop 0
	v_addc_co_u32_e32 v23, vcc, 0, v1, vcc
	v_add_co_u32_e32 v24, vcc, s45, v0
	global_load_ushort v7, v[4:5], off offset:2048 nt
	global_load_ushort v49, v[14:15], off offset:-4096 nt
	global_load_ushort v44, v[14:15], off nt
	global_load_ushort v47, v[14:15], off offset:1024 nt
	s_nop 0
	global_load_ushort v14, v[14:15], off offset:2048 nt
	s_nop 0
	global_load_ushort v41, v[22:23], off offset:-4096 nt
	global_load_ushort v39, v[22:23], off nt
	global_load_ushort v42, v[22:23], off offset:1024 nt
	v_addc_co_u32_e32 v25, vcc, 0, v1, vcc
	v_add_co_u32_e32 v26, vcc, s50, v0
	global_load_ushort v55, v[2:3], off offset:1024 nt
	global_load_ushort v18, v[2:3], off offset:2048 nt
	global_load_ushort v54, v[16:17], off offset:1024 nt
	s_nop 0
	global_load_ushort v17, v[16:17], off offset:2048 nt
	s_nop 0
	global_load_ushort v50, v[20:21], off offset:1024 nt
	global_load_ushort v15, v[20:21], off offset:2048 nt
	global_load_ushort v43, v[24:25], off offset:1024 nt
	global_load_ushort v16, v[24:25], off offset:2048 nt
	v_addc_co_u32_e32 v27, vcc, 0, v1, vcc
	v_add_co_u32_e32 v24, vcc, s51, v0
	v_readlane_b32 s78, v236, 13
	s_nop 0
	v_addc_co_u32_e32 v25, vcc, 0, v1, vcc
	v_add_co_u32_e32 v28, vcc, s54, v0
	v_readlane_b32 s79, v236, 14
	s_nop 0
	v_addc_co_u32_e32 v29, vcc, 0, v1, vcc
	global_load_ushort v19, v[22:23], off offset:2048 nt
	global_load_ushort v38, v[26:27], off offset:-4096 nt
	global_load_ushort v37, v[26:27], off nt
	global_load_ushort v46, v[26:27], off offset:1024 nt
	global_load_ushort v20, v[26:27], off offset:2048 nt
	global_load_ushort v36, v[28:29], off offset:-4096 nt
	global_load_ushort v35, v[28:29], off nt
	global_load_ushort v3, v[28:29], off offset:1024 nt
	v_add_co_u32_e32 v26, vcc, s55, v0
	v_readlane_b32 s80, v236, 15
	s_nop 0
	v_addc_co_u32_e32 v27, vcc, 0, v1, vcc
	v_add_co_u32_e32 v22, vcc, s56, v0
	v_readlane_b32 s81, v236, 16
	s_nop 0
	v_addc_co_u32_e32 v23, vcc, 0, v1, vcc
	global_load_ushort v21, v[28:29], off offset:2048 nt
	global_load_ushort v34, v[22:23], off offset:-4096 nt
	global_load_ushort v32, v[22:23], off nt
	global_load_ushort v2, v[22:23], off offset:1024 nt
	s_nop 0
	global_load_ushort v22, v[22:23], off offset:2048 nt
	v_add_co_u32_e32 v28, vcc, s57, v0
	v_readlane_b32 s82, v236, 17
	s_nop 0
	v_addc_co_u32_e32 v29, vcc, 0, v1, vcc
	v_add_co_u32_e32 v58, vcc, 0xe000, v0
	v_readlane_b32 s83, v236, 18
	s_nop 0
	v_addc_co_u32_e32 v59, vcc, 0, v1, vcc
	v_add_co_u32_e32 v60, vcc, 0xf000, v0
	global_load_ushort v53, v[24:25], off offset:1024 nt
	s_nop 0
	global_load_ushort v25, v[24:25], off offset:2048 nt
	s_nop 0
	global_load_ushort v48, v[26:27], off offset:1024 nt
	global_load_ushort v24, v[26:27], off offset:2048 nt
	global_load_ushort v31, v[28:29], off nt
	global_load_ushort v6, v[28:29], off offset:1024 nt
	global_load_ushort v23, v[28:29], off offset:2048 nt
	global_load_ushort v30, v[58:59], off nt
	v_addc_co_u32_e32 v61, vcc, 0, v1, vcc
	global_load_ushort v40, v[4:5], off offset:-4096 nt
	global_load_ushort v45, v[4:5], off nt
	global_load_ushort v56, v[4:5], off offset:1024 nt
	s_nop 0
	global_load_ushort v5, v[58:59], off offset:1024 nt
	global_load_ushort v26, v[58:59], off offset:2048 nt
	global_load_ushort v29, v[60:61], off nt
	global_load_ushort v4, v[60:61], off offset:1024 nt
	global_load_ushort v27, v[60:61], off offset:2048 nt
	v_mov_b32_e32 v28, 0
	v_readlane_b32 s84, v236, 19
	v_readlane_b32 s85, v236, 20
	v_readlane_b32 s86, v236, 21
	v_readlane_b32 s87, v236, 22
	s_and_saveexec_b64 s[10:11], s[4:5]
	s_cbranch_execz .LBB0_370
	global_load_ushort v28, v[0:1], off offset:2048 nt
	s_nop 0
	global_load_ushort v0, v[0:1], off nt
	s_waitcnt vmcnt(1)
	v_lshlrev_b32_e32 v28, 16, v28
	s_waitcnt vmcnt(0)
	v_lshlrev_b32_e32 v71, 16, v0

; __device__ __forceinline__ unsigned cvt_pk_bf16(float lo, float hi) { f32x2 f = {lo, hi}; bf16x2_t v = __builtin_convertvector(f, bf16x2_t); return __builtin_bit_cast(unsigned, v); }
;     __device__ __forceinline__ void operator()(const f32x4 (&acc)[2][2][4][2], const Unit& u, int wr, int wc, int fr, int fq) const {
;         const int row0 = u.pm * 256 + wr * 64 + fr; const int col0 = u.pn * 256 + wc * 32 + 4 * fq;
; #pragma unroll
;         for (int ai = 0; ai < 2; ++ai) {
;             f32x4 rr[4][2][2];
; #pragma unroll
;             for (int m = 0; m < 4; ++m) {
;                 const int row = row0 + ai * 128 + m * 16;
;                 const float* rrow = (row < NTOKP ? rp + (size_t)row * D : rs + (size_t)(row - NTOKP) * D) + col0;
; #pragma unroll
;                 for (int bj = 0; bj < 2; ++bj)
; #pragma unroll
;                     for (int n = 0; n < 2; ++n) rr[m][bj][n] = *(const f32x4*)(rrow + bj * 128 + n * 16);
;             }
; #pragma unroll
;             for (int m = 0; m < 4; ++m) {
;                 const int row = row0 + ai * 128 + m * 16; float* orow = out + (size_t)row * D + col0; float ss = 0.f;
; #pragma unroll
;                 for (int bj = 0; bj < 2; ++bj)
; #pragma unroll
;                     for (int n = 0; n < 2; ++n) {
;                         const f32x4 x = rr[m][bj][n] + acc[ai][bj][m][n];
;                         *(f32x4*)(orow + bj * 128 + n * 16) = x; ss += (x[0] * x[0] + x[1] * x[1]) + (x[2] * x[2] + x[3] * x[3]);
;                         if (xb) { u32x2 w; w.x = cvt_pk_bf16(x[0], x[1]); w.y = cvt_pk_bf16(x[2], x[3]); *(u32x2*)(xb + (size_t)row * D + col0 + bj * 128 + n * 16) = w; }
;                     }
;                 if (ssq) { ss += __shfl_xor(ss, 16); ss += __shfl_xor(ss, 32); if (fq == 0) ssq[row * 16 + u.pn * 4 + wc] = ss; }
;             }
.LBB0_922:
	v_lshl_add_u32 v192, s30, 8, v201
	v_add_u32_e32 v128, 0xffff8000, v192
	v_ashrrev_i32_e32 v193, 31, v192
	v_cmp_gt_i32_e32 vcc, s57, v192
	v_lshl_or_b32 v188, s28, 8, v203
	v_mov_b32_e32 v138, s41
	v_cndmask_b32_e32 v129, 0, v193, vcc
	v_cndmask_b32_e32 v128, v128, v192, vcc
	v_mov_b32_e32 v139, s37
	v_mov_b32_e32 v140, s40
	v_mov_b32_e32 v141, s36
	v_ashrrev_i32_e32 v189, 31, v188
	v_cndmask_b32_e32 v131, v138, v139, vcc
	v_cndmask_b32_e32 v130, v140, v141, vcc
	v_lshlrev_b64 v[128:129], 12, v[128:129]
	v_lshl_add_u64 v[128:129], v[130:131], 0, v[128:129]
	v_lshlrev_b64 v[190:191], 2, v[188:189]
	v_lshl_add_u64 v[128:129], v[128:129], 0, v[190:191]
	global_load_dwordx4 v[208:211], v[128:129], off nt
	global_load_dwordx4 v[212:215], v[128:129], off offset:64 nt
	global_load_dwordx4 v[216:219], v[128:129], off offset:512 nt
	global_load_dwordx4 v[220:223], v[128:129], off offset:576 nt
	v_or_b32_e32 v198, 16, v192
	v_add_u32_e32 v130, 0xffff8010, v192
	v_or_b32_e32 v196, 32, v192
	v_ashrrev_i32_e32 v199, 31, v198
	v_cmp_gt_i32_e32 vcc, s57, v198
	v_add_u32_e32 v134, 0xffff8020, v192
	v_or_b32_e32 v194, 48, v192
	v_ashrrev_i32_e32 v197, 31, v196
	v_cndmask_b32_e32 v131, 0, v199, vcc
	v_cndmask_b32_e32 v130, v130, v198, vcc
	v_cndmask_b32_e32 v133, v138, v139, vcc
	v_cndmask_b32_e32 v132, v140, v141, vcc
	v_cmp_gt_i32_e32 vcc, s57, v196
	v_add_u32_e32 v136, 0xffff8030, v192
	v_ashrrev_i32_e32 v195, 31, v194
	v_cndmask_b32_e32 v135, 0, v197, vcc
	v_cndmask_b32_e32 v134, v134, v196, vcc
	v_cndmask_b32_e32 v129, v138, v139, vcc
	v_cndmask_b32_e32 v128, v140, v141, vcc
	v_cmp_gt_i32_e32 vcc, s57, v194
	v_lshlrev_b64 v[130:131], 12, v[130:131]
	v_lshlrev_b64 v[134:135], 12, v[134:135]
	v_cndmask_b32_e32 v137, 0, v195, vcc
	v_cndmask_b32_e32 v136, v136, v194, vcc
	v_cndmask_b32_e32 v139, v138, v139, vcc
	v_cndmask_b32_e32 v138, v140, v141, vcc
	v_lshlrev_b64 v[136:137], 12, v[136:137]
	v_lshl_add_u64 v[130:131], v[132:133], 0, v[130:131]
	v_lshl_add_u64 v[128:129], v[128:129], 0, v[134:135]
	v_lshl_add_u64 v[132:133], v[138:139], 0, v[136:137]
	v_lshl_add_u64 v[130:131], v[130:131], 0, v[190:191]
	v_lshl_add_u64 v[128:129], v[128:129], 0, v[190:191]
	v_lshl_add_u64 v[224:225], v[132:133], 0, v[190:191]
	global_load_dwordx4 v[172:175], v[130:131], off nt
	global_load_dwordx4 v[168:171], v[130:131], off offset:64 nt
	global_load_dwordx4 v[164:167], v[130:131], off offset:512 nt
	global_load_dwordx4 v[160:163], v[130:131], off offset:576 nt
	global_load_dwordx4 v[156:159], v[128:129], off nt
	global_load_dwordx4 v[152:155], v[128:129], off offset:64 nt
	global_load_dwordx4 v[148:151], v[128:129], off offset:512 nt
	global_load_dwordx4 v[144:147], v[128:129], off offset:576 nt
	global_load_dwordx4 v[140:143], v[224:225], off nt
	global_load_dwordx4 v[136:139], v[224:225], off offset:64 nt
	global_load_dwordx4 v[132:135], v[224:225], off offset:512 nt
	s_nop 0
	global_load_dwordx4 v[128:131], v[224:225], off offset:576 nt
	v_lshlrev_b64 v[224:225], 12, v[192:193]
	v_lshlrev_b64 v[226:227], 11, v[192:193]
	v_lshl_add_u64 v[224:225], s[90:91], 0, v[224:225]
	v_lshl_add_u64 v[226:227], s[10:11], 0, v[226:227]
	v_lshl_add_u64 v[224:225], v[224:225], 0, v[190:191]
	v_lshl_add_u64 v[226:227], v[188:189], 1, v[226:227]
	s_lshl_b32 s21, s28, 2
	s_or_b32 s21, s21, s53
	s_waitcnt vmcnt(0)
	v_pk_add_f32 v[126:127], v[126:127], v[210:211]
	v_pk_add_f32 v[124:125], v[124:125], v[208:209]
	v_pk_add_f32 v[120:121], v[120:121], v[212:213]
	v_pk_add_f32 v[122:123], v[122:123], v[214:215]
	global_store_dwordx4 v[224:225], v[124:127], off
	v_mul_f32_e32 v193, v125, v125
	v_mul_f32_e32 v210, v127, v127
	v_cvt_pk_bf16_f32 v208, v124, v125
	v_cvt_pk_bf16_f32 v209, v126, v127
	v_mul_f32_e32 v125, v121, v121
	v_fmac_f32_e32 v210, v126, v126
	global_store_dwordx2 v[226:227], v[208:209], off
	global_store_dwordx4 v[224:225], v[120:123], off offset:64
	v_fmac_f32_e32 v125, v120, v120
	v_mul_f32_e32 v126, v123, v123
	v_cvt_pk_bf16_f32 v120, v120, v121
	v_cvt_pk_bf16_f32 v121, v122, v123
	v_pk_add_f32 v[118:119], v[118:119], v[218:219]
	v_pk_add_f32 v[116:117], v[116:117], v[216:217]
	v_fmac_f32_e32 v193, v124, v124
	v_fmac_f32_e32 v126, v122, v122
	global_store_dwordx2 v[226:227], v[120:121], off offset:32
	v_mul_f32_e32 v120, v117, v117
	v_mul_f32_e32 v121, v119, v119
	v_add_f32_e32 v124, v193, v210
	v_add_f32_e32 v125, v125, v126
	v_fmac_f32_e32 v120, v116, v116
	v_fmac_f32_e32 v121, v118, v118
	v_add_f32_e32 v124, v124, v125
	v_add_f32_e32 v120, v120, v121
	v_add_f32_e32 v120, v124, v120
	v_pk_add_f32 v[124:125], v[114:115], v[222:223]
	v_pk_add_f32 v[122:123], v[112:113], v[220:221]
	v_mul_f32_e32 v113, v125, v125
	v_mul_f32_e32 v112, v123, v123
	v_fmac_f32_e32 v112, v122, v122
	v_fmac_f32_e32 v113, v124, v124
	v_add_f32_e32 v112, v112, v113
	v_and_b32_e32 v113, 64, v207
	v_add_f32_e32 v114, v120, v112
	v_xor_b32_e32 v112, 16, v207
	v_add_u32_e32 v115, 64, v113
	v_cmp_lt_i32_e32 vcc, v112, v115
	v_cvt_pk_bf16_f32 v113, v118, v119
	global_store_dwordx4 v[224:225], v[116:119], off offset:512
	v_cndmask_b32_e32 v112, v207, v112, vcc
	v_lshlrev_b32_e32 v120, 2, v112
	ds_bpermute_b32 v121, v120, v114
	v_cvt_pk_bf16_f32 v112, v116, v117
	global_store_dwordx2 v[226:227], v[112:113], off offset:256
	v_xor_b32_e32 v113, 32, v207
	v_cmp_lt_i32_e32 vcc, v113, v115
	s_waitcnt lgkmcnt(0)
	v_add_f32_e32 v112, v114, v121
	v_cvt_pk_bf16_f32 v114, v122, v123
	v_cndmask_b32_e32 v113, v207, v113, vcc
	v_lshlrev_b32_e32 v121, 2, v113
	ds_bpermute_b32 v113, v121, v112
	v_cvt_pk_bf16_f32 v115, v124, v125
	global_store_dwordx4 v[224:225], v[122:125], off offset:576
	global_store_dwordx2 v[226:227], v[114:115], off offset:288
	s_and_saveexec_b64 s[28:29], s[4:5]
	s_cbranch_execz .LBB0_924
	v_lshl_add_u32 v114, v192, 4, s21
	v_ashrrev_i32_e32 v115, 31, v114
	v_lshl_add_u64 v[114:115], v[114:115], 2, s[12:13]
	s_waitcnt lgkmcnt(0)
	v_add_f32_e32 v112, v112, v113
	global_store_dword v[114:115], v112, off

; __device__ __forceinline__ unsigned cvt_pk_bf16(float lo, float hi) { f32x2 f = {lo, hi}; bf16x2_t v = __builtin_convertvector(f, bf16x2_t); return __builtin_bit_cast(unsigned, v); }
;     __device__ __forceinline__ void operator()(const f32x4 (&acc)[2][2][4][2], const Unit& u, int wr, int wc, int fr, int fq) const {
;         const int row0 = u.pm * 256 + wr * 64 + fr; const int col0 = u.pn * 256 + wc * 32 + 4 * fq;
; #pragma unroll
;         for (int ai = 0; ai < 2; ++ai) {
;             f32x4 rr[4][2][2];
; #pragma unroll
;             for (int m = 0; m < 4; ++m) {
;                 const int row = row0 + ai * 128 + m * 16;
;                 const float* rrow = (row < NTOKP ? rp + (size_t)row * D : rs + (size_t)(row - NTOKP) * D) + col0;
; #pragma unroll
;                 for (int bj = 0; bj < 2; ++bj)
; #pragma unroll
;                     for (int n = 0; n < 2; ++n) rr[m][bj][n] = *(const f32x4*)(rrow + bj * 128 + n * 16);
;             }
; #pragma unroll
;             for (int m = 0; m < 4; ++m) {
;                 const int row = row0 + ai * 128 + m * 16; float* orow = out + (size_t)row * D + col0; float ss = 0.f;
; #pragma unroll
;                 for (int bj = 0; bj < 2; ++bj)
; #pragma unroll
;                     for (int n = 0; n < 2; ++n) {
;                         const f32x4 x = rr[m][bj][n] + acc[ai][bj][m][n];
;                         *(f32x4*)(orow + bj * 128 + n * 16) = x; ss += (x[0] * x[0] + x[1] * x[1]) + (x[2] * x[2] + x[3] * x[3]);
;                         if (xb) { u32x2 w; w.x = cvt_pk_bf16(x[0], x[1]); w.y = cvt_pk_bf16(x[2], x[3]); *(u32x2*)(xb + (size_t)row * D + col0 + bj * 128 + n * 16) = w; }
;                     }
;                 if (ssq) { ss += __shfl_xor(ss, 16); ss += __shfl_xor(ss, 32); if (fq == 0) ssq[row * 16 + u.pn * 4 + wc] = ss; }
;             }
.LBB0_930:
	s_or_b64 exec, exec, s[28:29]
	v_add_u32_e32 v118, 0x80, v192
	v_ashrrev_i32_e32 v119, 31, v118
	v_add_u32_e32 v64, 0xffff8080, v192
	v_cmp_gt_i32_e32 vcc, s61, v192
	v_mov_b32_e32 v68, s41
	v_mov_b32_e32 v69, s37
	s_waitcnt lgkmcnt(0)
	v_cndmask_b32_e32 v65, 0, v119, vcc
	v_cndmask_b32_e32 v64, v64, v118, vcc
	v_mov_b32_e32 v70, s40
	v_mov_b32_e32 v71, s36
	v_cndmask_b32_e32 v67, v68, v69, vcc
	v_cndmask_b32_e32 v66, v70, v71, vcc
	v_lshlrev_b64 v[64:65], 12, v[64:65]
	v_lshl_add_u64 v[64:65], v[66:67], 0, v[64:65]
	v_lshl_add_u64 v[64:65], v[64:65], 0, v[190:191]
	global_load_dwordx4 v[122:125], v[64:65], off nt
	global_load_dwordx4 v[126:129], v[64:65], off offset:64 nt
	global_load_dwordx4 v[130:133], v[64:65], off offset:512 nt
	global_load_dwordx4 v[134:137], v[64:65], off offset:576 nt
	v_add_u32_e32 v116, 0x90, v192
	v_ashrrev_i32_e32 v117, 31, v116
	v_add_u32_e32 v64, 0xffff8090, v192
	v_cmp_gt_i32_e32 vcc, s62, v192
	v_add_u32_e32 v114, 0xa0, v192
	v_ashrrev_i32_e32 v115, 31, v114
	v_cndmask_b32_e32 v65, 0, v117, vcc
	v_cndmask_b32_e32 v64, v64, v116, vcc
	v_cndmask_b32_e32 v67, v68, v69, vcc
	v_cndmask_b32_e32 v66, v70, v71, vcc
	v_lshlrev_b64 v[64:65], 12, v[64:65]
	v_lshl_add_u64 v[64:65], v[66:67], 0, v[64:65]
	v_lshl_add_u64 v[64:65], v[64:65], 0, v[190:191]
	global_load_dwordx4 v[108:111], v[64:65], off nt
	global_load_dwordx4 v[104:107], v[64:65], off offset:64 nt
	global_load_dwordx4 v[100:103], v[64:65], off offset:512 nt
	global_load_dwordx4 v[96:99], v[64:65], off offset:576 nt
	v_add_u32_e32 v64, 0xffff80a0, v192
	v_cmp_gt_i32_e32 vcc, s63, v192
	v_add_u32_e32 v112, 0xb0, v192
	v_ashrrev_i32_e32 v113, 31, v112
	v_cndmask_b32_e32 v65, 0, v115, vcc
	v_cndmask_b32_e32 v64, v64, v114, vcc
	v_cndmask_b32_e32 v67, v68, v69, vcc
	v_cndmask_b32_e32 v66, v70, v71, vcc
	v_lshlrev_b64 v[64:65], 12, v[64:65]
	v_lshl_add_u64 v[64:65], v[66:67], 0, v[64:65]
	v_lshl_add_u64 v[64:65], v[64:65], 0, v[190:191]
	global_load_dwordx4 v[92:95], v[64:65], off nt
	global_load_dwordx4 v[88:91], v[64:65], off offset:64 nt
	global_load_dwordx4 v[84:87], v[64:65], off offset:512 nt
	global_load_dwordx4 v[80:83], v[64:65], off offset:576 nt
	v_add_u32_e32 v64, 0xffff80b0, v192
	v_cmp_gt_i32_e32 vcc, s64, v192
	v_lshlrev_b64 v[138:139], 12, v[118:119]
	v_lshl_add_u64 v[138:139], s[90:91], 0, v[138:139]
	v_cndmask_b32_e32 v65, 0, v113, vcc
	v_cndmask_b32_e32 v64, v64, v112, vcc
	v_cndmask_b32_e32 v67, v68, v69, vcc
	v_cndmask_b32_e32 v66, v70, v71, vcc
	v_lshlrev_b64 v[64:65], 12, v[64:65]
	v_lshl_add_u64 v[64:65], v[66:67], 0, v[64:65]
	v_lshl_add_u64 v[64:65], v[64:65], 0, v[190:191]
	global_load_dwordx4 v[76:79], v[64:65], off nt
	global_load_dwordx4 v[72:75], v[64:65], off offset:64 nt
	global_load_dwordx4 v[68:71], v[64:65], off offset:512 nt
	s_nop 0
	global_load_dwordx4 v[64:67], v[64:65], off offset:576 nt
	v_lshlrev_b64 v[140:141], 11, v[118:119]
	v_lshl_add_u64 v[138:139], v[138:139], 0, v[190:191]
	v_lshl_add_u64 v[140:141], s[10:11], 0, v[140:141]
	v_lshl_add_u64 v[140:141], v[188:189], 1, v[140:141]
	s_waitcnt vmcnt(15)
	v_pk_add_f32 v[62:63], v[62:63], v[124:125]
	v_pk_add_f32 v[60:61], v[60:61], v[122:123]
	s_waitcnt vmcnt(14)
	v_pk_add_f32 v[58:59], v[58:59], v[128:129]
	v_pk_add_f32 v[56:57], v[56:57], v[126:127]
	global_store_dwordx4 v[138:139], v[60:63], off
	v_mul_f32_e32 v119, v61, v61
	v_mul_f32_e32 v125, v63, v63
	v_cvt_pk_bf16_f32 v122, v60, v61
	v_cvt_pk_bf16_f32 v123, v62, v63
	v_mul_f32_e32 v61, v57, v57
	v_mul_f32_e32 v63, v59, v59
	v_fmac_f32_e32 v119, v60, v60
	v_fmac_f32_e32 v125, v62, v62
	v_fmac_f32_e32 v61, v56, v56
	v_fmac_f32_e32 v63, v58, v58
	v_cvt_pk_bf16_f32 v124, v56, v57
	global_store_dwordx2 v[140:141], v[122:123], off
	global_store_dwordx4 v[138:139], v[56:59], off offset:64
	s_waitcnt vmcnt(16)
	v_pk_add_f32 v[54:55], v[54:55], v[132:133]
	v_pk_add_f32 v[52:53], v[52:53], v[130:131]
	v_add_f32_e32 v56, v119, v125
	v_add_f32_e32 v57, v61, v63
	v_add_f32_e32 v56, v56, v57
	v_cvt_pk_bf16_f32 v125, v58, v59
	v_mul_f32_e32 v57, v53, v53
	v_mul_f32_e32 v58, v55, v55
	v_fmac_f32_e32 v57, v52, v52
	v_fmac_f32_e32 v58, v54, v54
	v_add_f32_e32 v57, v57, v58
	v_add_f32_e32 v60, v56, v57
	s_waitcnt vmcnt(15)
	v_pk_add_f32 v[58:59], v[50:51], v[136:137]
	v_pk_add_f32 v[56:57], v[48:49], v[134:135]
	v_mul_f32_e32 v49, v59, v59
	v_mul_f32_e32 v48, v57, v57
	v_fmac_f32_e32 v48, v56, v56
	v_fmac_f32_e32 v49, v58, v58
	v_add_f32_e32 v48, v48, v49
	v_add_f32_e32 v50, v60, v48
	ds_bpermute_b32 v51, v120, v50
	v_cvt_pk_bf16_f32 v48, v52, v53
	v_cvt_pk_bf16_f32 v49, v54, v55
	global_store_dwordx2 v[140:141], v[124:125], off offset:32
	global_store_dwordx4 v[138:139], v[52:55], off offset:512
	global_store_dwordx2 v[140:141], v[48:49], off offset:256
	s_waitcnt lgkmcnt(0)
	v_add_f32_e32 v48, v50, v51
	ds_bpermute_b32 v49, v121, v48
	v_cvt_pk_bf16_f32 v50, v56, v57
	v_cvt_pk_bf16_f32 v51, v58, v59
	global_store_dwordx4 v[138:139], v[56:59], off offset:576
	global_store_dwordx2 v[140:141], v[50:51], off offset:288
	s_and_saveexec_b64 s[28:29], s[4:5]
	s_cbranch_execz .LBB0_932
	v_lshl_add_u32 v50, v118, 4, s21
	v_ashrrev_i32_e32 v51, 31, v50
	v_lshl_add_u64 v[50:51], v[50:51], 2, s[12:13]
	s_waitcnt lgkmcnt(0)
	v_add_f32_e32 v48, v48, v49
	global_store_dword v[50:51], v48, off

; __device__ __forceinline__ unsigned cvt_pk_bf16(float lo, float hi) { f32x2 f = {lo, hi}; bf16x2_t v = __builtin_convertvector(f, bf16x2_t); return __builtin_bit_cast(unsigned, v); }
;     __device__ __forceinline__ void operator()(const f32x4 (&acc)[2][2][4][2], const Unit& u, int wr, int wc, int fr, int fq) const {
;         const int row0 = u.pm * 256 + wr * 64 + fr; const int col0 = u.pn * 256 + wc * 32 + 4 * fq;
; #pragma unroll
;         for (int ai = 0; ai < 2; ++ai) {
;             f32x4 rr[4][2][2];
; #pragma unroll
;             for (int m = 0; m < 4; ++m) {
;                 const int row = row0 + ai * 128 + m * 16;
;                 const float* rrow = (row < NTOKP ? rp + (size_t)row * D : rs + (size_t)(row - NTOKP) * D) + col0;
; #pragma unroll
;                 for (int bj = 0; bj < 2; ++bj)
; #pragma unroll
;                     for (int n = 0; n < 2; ++n) rr[m][bj][n] = *(const f32x4*)(rrow + bj * 128 + n * 16);
;             }
; #pragma unroll
;             for (int m = 0; m < 4; ++m) {
;                 const int row = row0 + ai * 128 + m * 16; float* orow = out + (size_t)row * D + col0; float ss = 0.f;
; #pragma unroll
;                 for (int bj = 0; bj < 2; ++bj)
; #pragma unroll
;                     for (int n = 0; n < 2; ++n) {
;                         const f32x4 x = rr[m][bj][n] + acc[ai][bj][m][n];
;                         *(f32x4*)(orow + bj * 128 + n * 16) = x; ss += (x[0] * x[0] + x[1] * x[1]) + (x[2] * x[2] + x[3] * x[3]);
;                         if (xb) { u32x2 w; w.x = cvt_pk_bf16(x[0], x[1]); w.y = cvt_pk_bf16(x[2], x[3]); *(u32x2*)(xb + (size_t)row * D + col0 + bj * 128 + n * 16) = w; }
;                     }
;                 if (ssq) { ss += __shfl_xor(ss, 16); ss += __shfl_xor(ss, 32); if (fq == 0) ssq[row * 16 + u.pn * 4 + wc] = ss; }
;             }
.LBB0_1196:
	v_lshl_add_u32 v192, s36, 8, v201
	v_add_u32_e32 v128, 0xffff8000, v192
	v_ashrrev_i32_e32 v193, 31, v192
	v_cmp_gt_i32_e32 vcc, s55, v192
	v_lshl_or_b32 v188, s30, 8, v203
	v_mov_b32_e32 v138, s11
	v_cndmask_b32_e32 v129, 0, v193, vcc
	v_cndmask_b32_e32 v128, v128, v192, vcc
	v_mov_b32_e32 v139, s91
	v_mov_b32_e32 v140, s10
	v_mov_b32_e32 v141, s90
	v_ashrrev_i32_e32 v189, 31, v188
	v_cndmask_b32_e32 v131, v138, v139, vcc
	v_cndmask_b32_e32 v130, v140, v141, vcc
	v_lshlrev_b64 v[128:129], 12, v[128:129]
	v_lshl_add_u64 v[128:129], v[130:131], 0, v[128:129]
	v_lshlrev_b64 v[190:191], 2, v[188:189]
	v_lshl_add_u64 v[128:129], v[128:129], 0, v[190:191]
	global_load_dwordx4 v[208:211], v[128:129], off nt
	global_load_dwordx4 v[212:215], v[128:129], off offset:64 nt
	global_load_dwordx4 v[216:219], v[128:129], off offset:512 nt
	global_load_dwordx4 v[220:223], v[128:129], off offset:576 nt
	v_or_b32_e32 v198, 16, v192
	v_add_u32_e32 v130, 0xffff8010, v192
	v_or_b32_e32 v196, 32, v192
	v_ashrrev_i32_e32 v199, 31, v198
	v_cmp_gt_i32_e32 vcc, s55, v198
	v_add_u32_e32 v134, 0xffff8020, v192
	v_or_b32_e32 v194, 48, v192
	v_ashrrev_i32_e32 v197, 31, v196
	v_cndmask_b32_e32 v131, 0, v199, vcc
	v_cndmask_b32_e32 v130, v130, v198, vcc
	v_cndmask_b32_e32 v133, v138, v139, vcc
	v_cndmask_b32_e32 v132, v140, v141, vcc
	v_cmp_gt_i32_e32 vcc, s55, v196
	v_add_u32_e32 v136, 0xffff8030, v192
	v_ashrrev_i32_e32 v195, 31, v194
	v_cndmask_b32_e32 v135, 0, v197, vcc
	v_cndmask_b32_e32 v134, v134, v196, vcc
	v_cndmask_b32_e32 v129, v138, v139, vcc
	v_cndmask_b32_e32 v128, v140, v141, vcc
	v_cmp_gt_i32_e32 vcc, s55, v194
	v_lshlrev_b64 v[130:131], 12, v[130:131]
	v_lshlrev_b64 v[134:135], 12, v[134:135]
	v_cndmask_b32_e32 v137, 0, v195, vcc
	v_cndmask_b32_e32 v136, v136, v194, vcc
	v_cndmask_b32_e32 v139, v138, v139, vcc
	v_cndmask_b32_e32 v138, v140, v141, vcc
	v_lshlrev_b64 v[136:137], 12, v[136:137]
	v_lshl_add_u64 v[130:131], v[132:133], 0, v[130:131]
	v_lshl_add_u64 v[128:129], v[128:129], 0, v[134:135]
	v_lshl_add_u64 v[132:133], v[138:139], 0, v[136:137]
	v_lshl_add_u64 v[130:131], v[130:131], 0, v[190:191]
	v_lshl_add_u64 v[128:129], v[128:129], 0, v[190:191]
	v_lshl_add_u64 v[224:225], v[132:133], 0, v[190:191]
	global_load_dwordx4 v[172:175], v[130:131], off nt
	global_load_dwordx4 v[168:171], v[130:131], off offset:64 nt
	global_load_dwordx4 v[164:167], v[130:131], off offset:512 nt
	global_load_dwordx4 v[160:163], v[130:131], off offset:576 nt
	global_load_dwordx4 v[156:159], v[128:129], off nt
	global_load_dwordx4 v[152:155], v[128:129], off offset:64 nt
	global_load_dwordx4 v[148:151], v[128:129], off offset:512 nt
	global_load_dwordx4 v[144:147], v[128:129], off offset:576 nt
	global_load_dwordx4 v[140:143], v[224:225], off nt
	global_load_dwordx4 v[136:139], v[224:225], off offset:64 nt
	global_load_dwordx4 v[132:135], v[224:225], off offset:512 nt
	s_nop 0
	global_load_dwordx4 v[128:131], v[224:225], off offset:576 nt
	v_lshlrev_b64 v[224:225], 12, v[192:193]
	v_lshlrev_b64 v[226:227], 11, v[192:193]
	v_lshl_add_u64 v[224:225], s[90:91], 0, v[224:225]
	v_lshl_add_u64 v[226:227], s[12:13], 0, v[226:227]
	v_lshl_add_u64 v[224:225], v[224:225], 0, v[190:191]
	v_lshl_add_u64 v[226:227], v[188:189], 1, v[226:227]
	s_lshl_b32 s23, s30, 2
	s_or_b32 s23, s23, s51
	s_waitcnt vmcnt(0)
	v_pk_add_f32 v[126:127], v[126:127], v[210:211]
	v_pk_add_f32 v[124:125], v[124:125], v[208:209]
	v_pk_add_f32 v[120:121], v[120:121], v[212:213]
	v_pk_add_f32 v[122:123], v[122:123], v[214:215]
	global_store_dwordx4 v[224:225], v[124:127], off
	v_mul_f32_e32 v193, v125, v125
	v_mul_f32_e32 v210, v127, v127
	v_cvt_pk_bf16_f32 v208, v124, v125
	v_cvt_pk_bf16_f32 v209, v126, v127
	v_mul_f32_e32 v125, v121, v121
	v_fmac_f32_e32 v210, v126, v126
	global_store_dwordx2 v[226:227], v[208:209], off
	global_store_dwordx4 v[224:225], v[120:123], off offset:64
	v_fmac_f32_e32 v125, v120, v120
	v_mul_f32_e32 v126, v123, v123
	v_cvt_pk_bf16_f32 v120, v120, v121
	v_cvt_pk_bf16_f32 v121, v122, v123
	v_pk_add_f32 v[118:119], v[118:119], v[218:219]
	v_pk_add_f32 v[116:117], v[116:117], v[216:217]
	v_fmac_f32_e32 v193, v124, v124
	v_fmac_f32_e32 v126, v122, v122
	global_store_dwordx2 v[226:227], v[120:121], off offset:32
	v_mul_f32_e32 v120, v117, v117
	v_mul_f32_e32 v121, v119, v119
	v_add_f32_e32 v124, v193, v210
	v_add_f32_e32 v125, v125, v126
	v_fmac_f32_e32 v120, v116, v116
	v_fmac_f32_e32 v121, v118, v118
	v_add_f32_e32 v124, v124, v125
	v_add_f32_e32 v120, v120, v121
	v_add_f32_e32 v120, v124, v120
	v_pk_add_f32 v[124:125], v[114:115], v[222:223]
	v_pk_add_f32 v[122:123], v[112:113], v[220:221]
	v_mul_f32_e32 v113, v125, v125
	v_mul_f32_e32 v112, v123, v123
	v_fmac_f32_e32 v112, v122, v122
	v_fmac_f32_e32 v113, v124, v124
	v_add_f32_e32 v112, v112, v113
	v_and_b32_e32 v113, 64, v207
	v_add_f32_e32 v114, v120, v112
	v_xor_b32_e32 v112, 16, v207
	v_add_u32_e32 v115, 64, v113
	v_cmp_lt_i32_e32 vcc, v112, v115
	v_cvt_pk_bf16_f32 v113, v118, v119
	global_store_dwordx4 v[224:225], v[116:119], off offset:512
	v_cndmask_b32_e32 v112, v207, v112, vcc
	v_lshlrev_b32_e32 v120, 2, v112
	ds_bpermute_b32 v121, v120, v114
	v_cvt_pk_bf16_f32 v112, v116, v117
	global_store_dwordx2 v[226:227], v[112:113], off offset:256
	v_xor_b32_e32 v113, 32, v207
	v_cmp_lt_i32_e32 vcc, v113, v115
	s_waitcnt lgkmcnt(0)
	v_add_f32_e32 v112, v114, v121
	v_cvt_pk_bf16_f32 v114, v122, v123
	v_cndmask_b32_e32 v113, v207, v113, vcc
	v_lshlrev_b32_e32 v121, 2, v113
	ds_bpermute_b32 v113, v121, v112
	v_cvt_pk_bf16_f32 v115, v124, v125
	global_store_dwordx4 v[224:225], v[122:125], off offset:576
	global_store_dwordx2 v[226:227], v[114:115], off offset:288
	s_and_saveexec_b64 s[30:31], s[4:5]
	s_cbranch_execz .LBB0_1198
	v_lshl_add_u32 v114, v192, 4, s23
	v_ashrrev_i32_e32 v115, 31, v114
	v_lshl_add_u64 v[114:115], v[114:115], 2, s[16:17]
	s_waitcnt lgkmcnt(0)
	v_add_f32_e32 v112, v112, v113
	global_store_dword v[114:115], v112, off

; __device__ __forceinline__ unsigned cvt_pk_bf16(float lo, float hi) { f32x2 f = {lo, hi}; bf16x2_t v = __builtin_convertvector(f, bf16x2_t); return __builtin_bit_cast(unsigned, v); }
;     __device__ __forceinline__ void operator()(const f32x4 (&acc)[2][2][4][2], const Unit& u, int wr, int wc, int fr, int fq) const {
;         const int row0 = u.pm * 256 + wr * 64 + fr; const int col0 = u.pn * 256 + wc * 32 + 4 * fq;
; #pragma unroll
;         for (int ai = 0; ai < 2; ++ai) {
;             f32x4 rr[4][2][2];
; #pragma unroll
;             for (int m = 0; m < 4; ++m) {
;                 const int row = row0 + ai * 128 + m * 16;
;                 const float* rrow = (row < NTOKP ? rp + (size_t)row * D : rs + (size_t)(row - NTOKP) * D) + col0;
; #pragma unroll
;                 for (int bj = 0; bj < 2; ++bj)
; #pragma unroll
;                     for (int n = 0; n < 2; ++n) rr[m][bj][n] = *(const f32x4*)(rrow + bj * 128 + n * 16);
;             }
; #pragma unroll
;             for (int m = 0; m < 4; ++m) {
;                 const int row = row0 + ai * 128 + m * 16; float* orow = out + (size_t)row * D + col0; float ss = 0.f;
; #pragma unroll
;                 for (int bj = 0; bj < 2; ++bj)
; #pragma unroll
;                     for (int n = 0; n < 2; ++n) {
;                         const f32x4 x = rr[m][bj][n] + acc[ai][bj][m][n];
;                         *(f32x4*)(orow + bj * 128 + n * 16) = x; ss += (x[0] * x[0] + x[1] * x[1]) + (x[2] * x[2] + x[3] * x[3]);
;                         if (xb) { u32x2 w; w.x = cvt_pk_bf16(x[0], x[1]); w.y = cvt_pk_bf16(x[2], x[3]); *(u32x2*)(xb + (size_t)row * D + col0 + bj * 128 + n * 16) = w; }
;                     }
;                 if (ssq) { ss += __shfl_xor(ss, 16); ss += __shfl_xor(ss, 32); if (fq == 0) ssq[row * 16 + u.pn * 4 + wc] = ss; }
;             }
.LBB0_1204:
	s_or_b64 exec, exec, s[30:31]
	v_add_u32_e32 v118, 0x80, v192
	v_ashrrev_i32_e32 v119, 31, v118
	v_add_u32_e32 v64, 0xffff8080, v192
	v_cmp_gt_i32_e32 vcc, s59, v192
	v_mov_b32_e32 v68, s11
	v_mov_b32_e32 v69, s91
	s_waitcnt lgkmcnt(0)
	v_cndmask_b32_e32 v65, 0, v119, vcc
	v_cndmask_b32_e32 v64, v64, v118, vcc
	v_mov_b32_e32 v70, s10
	v_mov_b32_e32 v71, s90
	v_cndmask_b32_e32 v67, v68, v69, vcc
	v_cndmask_b32_e32 v66, v70, v71, vcc
	v_lshlrev_b64 v[64:65], 12, v[64:65]
	v_lshl_add_u64 v[64:65], v[66:67], 0, v[64:65]
	v_lshl_add_u64 v[64:65], v[64:65], 0, v[190:191]
	global_load_dwordx4 v[122:125], v[64:65], off nt
	global_load_dwordx4 v[126:129], v[64:65], off offset:64 nt
	global_load_dwordx4 v[130:133], v[64:65], off offset:512 nt
	global_load_dwordx4 v[134:137], v[64:65], off offset:576 nt
	v_add_u32_e32 v116, 0x90, v192
	v_ashrrev_i32_e32 v117, 31, v116
	v_add_u32_e32 v64, 0xffff8090, v192
	v_cmp_gt_i32_e32 vcc, s60, v192
	v_add_u32_e32 v114, 0xa0, v192
	v_ashrrev_i32_e32 v115, 31, v114
	v_cndmask_b32_e32 v65, 0, v117, vcc
	v_cndmask_b32_e32 v64, v64, v116, vcc
	v_cndmask_b32_e32 v67, v68, v69, vcc
	v_cndmask_b32_e32 v66, v70, v71, vcc
	v_lshlrev_b64 v[64:65], 12, v[64:65]
	v_lshl_add_u64 v[64:65], v[66:67], 0, v[64:65]
	v_lshl_add_u64 v[64:65], v[64:65], 0, v[190:191]
	global_load_dwordx4 v[108:111], v[64:65], off nt
	global_load_dwordx4 v[104:107], v[64:65], off offset:64 nt
	global_load_dwordx4 v[100:103], v[64:65], off offset:512 nt
	global_load_dwordx4 v[96:99], v[64:65], off offset:576 nt
	v_add_u32_e32 v64, 0xffff80a0, v192
	v_cmp_gt_i32_e32 vcc, s61, v192
	v_add_u32_e32 v112, 0xb0, v192
	v_ashrrev_i32_e32 v113, 31, v112
	v_cndmask_b32_e32 v65, 0, v115, vcc
	v_cndmask_b32_e32 v64, v64, v114, vcc
	v_cndmask_b32_e32 v67, v68, v69, vcc
	v_cndmask_b32_e32 v66, v70, v71, vcc
	v_lshlrev_b64 v[64:65], 12, v[64:65]
	v_lshl_add_u64 v[64:65], v[66:67], 0, v[64:65]
	v_lshl_add_u64 v[64:65], v[64:65], 0, v[190:191]
	global_load_dwordx4 v[92:95], v[64:65], off nt
	global_load_dwordx4 v[88:91], v[64:65], off offset:64 nt
	global_load_dwordx4 v[84:87], v[64:65], off offset:512 nt
	global_load_dwordx4 v[80:83], v[64:65], off offset:576 nt
	v_add_u32_e32 v64, 0xffff80b0, v192
	v_cmp_gt_i32_e32 vcc, s62, v192
	v_lshlrev_b64 v[138:139], 12, v[118:119]
	v_lshl_add_u64 v[138:139], s[90:91], 0, v[138:139]
	v_cndmask_b32_e32 v65, 0, v113, vcc
	v_cndmask_b32_e32 v64, v64, v112, vcc
	v_cndmask_b32_e32 v67, v68, v69, vcc
	v_cndmask_b32_e32 v66, v70, v71, vcc
	v_lshlrev_b64 v[64:65], 12, v[64:65]
	v_lshl_add_u64 v[64:65], v[66:67], 0, v[64:65]
	v_lshl_add_u64 v[64:65], v[64:65], 0, v[190:191]
	global_load_dwordx4 v[76:79], v[64:65], off nt
	global_load_dwordx4 v[72:75], v[64:65], off offset:64 nt
	global_load_dwordx4 v[68:71], v[64:65], off offset:512 nt
	s_nop 0
	global_load_dwordx4 v[64:67], v[64:65], off offset:576 nt
	v_lshlrev_b64 v[140:141], 11, v[118:119]
	v_lshl_add_u64 v[138:139], v[138:139], 0, v[190:191]
	v_lshl_add_u64 v[140:141], s[12:13], 0, v[140:141]
	v_lshl_add_u64 v[140:141], v[188:189], 1, v[140:141]
	s_waitcnt vmcnt(15)
	v_pk_add_f32 v[62:63], v[62:63], v[124:125]
	v_pk_add_f32 v[60:61], v[60:61], v[122:123]
	s_waitcnt vmcnt(14)
	v_pk_add_f32 v[58:59], v[58:59], v[128:129]
	v_pk_add_f32 v[56:57], v[56:57], v[126:127]
	global_store_dwordx4 v[138:139], v[60:63], off
	v_mul_f32_e32 v119, v61, v61
	v_mul_f32_e32 v125, v63, v63
	v_cvt_pk_bf16_f32 v122, v60, v61
	v_cvt_pk_bf16_f32 v123, v62, v63
	v_mul_f32_e32 v61, v57, v57
	v_mul_f32_e32 v63, v59, v59
	v_fmac_f32_e32 v119, v60, v60
	v_fmac_f32_e32 v125, v62, v62
	v_fmac_f32_e32 v61, v56, v56
	v_fmac_f32_e32 v63, v58, v58
	v_cvt_pk_bf16_f32 v124, v56, v57
	global_store_dwordx2 v[140:141], v[122:123], off
	global_store_dwordx4 v[138:139], v[56:59], off offset:64
	s_waitcnt vmcnt(16)
	v_pk_add_f32 v[54:55], v[54:55], v[132:133]
	v_pk_add_f32 v[52:53], v[52:53], v[130:131]
	v_add_f32_e32 v56, v119, v125
	v_add_f32_e32 v57, v61, v63
	v_add_f32_e32 v56, v56, v57
	v_cvt_pk_bf16_f32 v125, v58, v59
	v_mul_f32_e32 v57, v53, v53
	v_mul_f32_e32 v58, v55, v55
	v_fmac_f32_e32 v57, v52, v52
	v_fmac_f32_e32 v58, v54, v54
	v_add_f32_e32 v57, v57, v58
	v_add_f32_e32 v60, v56, v57
	s_waitcnt vmcnt(15)
	v_pk_add_f32 v[58:59], v[50:51], v[136:137]
	v_pk_add_f32 v[56:57], v[48:49], v[134:135]
	v_mul_f32_e32 v49, v59, v59
	v_mul_f32_e32 v48, v57, v57
	v_fmac_f32_e32 v48, v56, v56
	v_fmac_f32_e32 v49, v58, v58
	v_add_f32_e32 v48, v48, v49
	v_add_f32_e32 v50, v60, v48
	ds_bpermute_b32 v51, v120, v50
	v_cvt_pk_bf16_f32 v48, v52, v53
	v_cvt_pk_bf16_f32 v49, v54, v55
	global_store_dwordx2 v[140:141], v[124:125], off offset:32
	global_store_dwordx4 v[138:139], v[52:55], off offset:512
	global_store_dwordx2 v[140:141], v[48:49], off offset:256
	s_waitcnt lgkmcnt(0)
	v_add_f32_e32 v48, v50, v51
	ds_bpermute_b32 v49, v121, v48
	v_cvt_pk_bf16_f32 v50, v56, v57
	v_cvt_pk_bf16_f32 v51, v58, v59
	global_store_dwordx4 v[138:139], v[56:59], off offset:576
	global_store_dwordx2 v[140:141], v[50:51], off offset:288
	s_and_saveexec_b64 s[30:31], s[4:5]
	s_cbranch_execz .LBB0_1206
	v_lshl_add_u32 v50, v118, 4, s23
	v_ashrrev_i32_e32 v51, 31, v50
	v_lshl_add_u64 v[50:51], v[50:51], 2, s[16:17]
	s_waitcnt lgkmcnt(0)
	v_add_f32_e32 v48, v48, v49
	global_store_dword v[50:51], v48, off

;     __device__ __forceinline__ void operator()(const f32x4 (&acc)[2][2][4][2], const Unit& u, int wr, int wc, int fr, int fq) const {
;         const int row0 = u.pm * 256 + wr * 64 + fr; const int col0 = u.pn * 256 + wc * 32 + 4 * fq;
; #pragma unroll
;         for (int ai = 0; ai < 2; ++ai) {
;             f32x4 rr[4][2][2];
; #pragma unroll
;             for (int m = 0; m < 4; ++m) {
;                 const int row = row0 + ai * 128 + m * 16;
;                 const float* rrow = (row < NTOKP ? rp + (size_t)row * D : rs + (size_t)(row - NTOKP) * D) + col0;
; #pragma unroll
;                 for (int bj = 0; bj < 2; ++bj)
; #pragma unroll
;                     for (int n = 0; n < 2; ++n) rr[m][bj][n] = *(const f32x4*)(rrow + bj * 128 + n * 16);
;             }
; #pragma unroll
;             for (int m = 0; m < 4; ++m) {
;                 const int row = row0 + ai * 128 + m * 16; float* orow = out + (size_t)row * D + col0; float ss = 0.f;
; #pragma unroll
;                 for (int bj = 0; bj < 2; ++bj)
; #pragma unroll
;                     for (int n = 0; n < 2; ++n) {
;                         const f32x4 x = rr[m][bj][n] + acc[ai][bj][m][n];
;                         *(f32x4*)(orow + bj * 128 + n * 16) = x; ss += (x[0] * x[0] + x[1] * x[1]) + (x[2] * x[2] + x[3] * x[3]);
.LBB0_1375:
	v_lshl_add_u32 v142, s50, 8, v144
	v_add_u32_e32 v150, 0xffff8000, v142
	v_ashrrev_i32_e32 v143, 31, v142
	v_cmp_gt_i32_e32 vcc, s40, v142
	v_mov_b32_e32 v201, s9
	v_mov_b32_e32 v224, s91
	v_mov_b32_e32 v225, s8
	v_mov_b32_e32 v226, s90
	v_or_b32_e32 v198, 16, v142
	v_cndmask_b32_e32 v151, 0, v143, vcc
	v_cndmask_b32_e32 v150, v150, v142, vcc
	v_cndmask_b32_e32 v153, v201, v224, vcc
	v_cndmask_b32_e32 v152, v225, v226, vcc
	v_ashrrev_i32_e32 v199, 31, v198
	v_add_u32_e32 v166, 0xffff8010, v142
	v_cmp_gt_i32_e32 vcc, s40, v198
	v_lshl_or_b32 v140, s51, 8, v146
	v_ashrrev_i32_e32 v141, 31, v140
	v_cndmask_b32_e32 v167, 0, v199, vcc
	v_cndmask_b32_e32 v166, v166, v198, vcc
	v_lshlrev_b64 v[150:151], 12, v[150:151]
	v_cndmask_b32_e32 v169, v201, v224, vcc
	v_cndmask_b32_e32 v168, v225, v226, vcc
	v_lshlrev_b64 v[166:167], 12, v[166:167]
	v_or_b32_e32 v218, 32, v142
	v_lshl_add_u64 v[150:151], v[152:153], 0, v[150:151]
	v_lshlrev_b64 v[140:141], 2, v[140:141]
	v_lshl_add_u64 v[166:167], v[168:169], 0, v[166:167]
	v_ashrrev_i32_e32 v219, 31, v218
	v_add_u32_e32 v182, 0xffff8020, v142
	v_cmp_gt_i32_e32 vcc, s40, v218
	v_lshl_add_u64 v[162:163], v[150:151], 0, v[140:141]
	v_lshl_add_u64 v[178:179], v[166:167], 0, v[140:141]
	v_cndmask_b32_e32 v183, 0, v219, vcc
	v_cndmask_b32_e32 v182, v182, v218, vcc
	global_load_dwordx4 v[150:153], v[162:163], off nt
	global_load_dwordx4 v[154:157], v[162:163], off offset:64 nt
	global_load_dwordx4 v[158:161], v[162:163], off offset:512 nt
	s_nop 0
	global_load_dwordx4 v[162:165], v[162:163], off offset:576 nt
	s_nop 0
	global_load_dwordx4 v[166:169], v[178:179], off nt
	global_load_dwordx4 v[170:173], v[178:179], off offset:64 nt
	global_load_dwordx4 v[174:177], v[178:179], off offset:512 nt
	s_nop 0
	global_load_dwordx4 v[178:181], v[178:179], off offset:576 nt
	v_cndmask_b32_e32 v185, v201, v224, vcc
	v_cndmask_b32_e32 v184, v225, v226, vcc
	v_lshlrev_b64 v[182:183], 12, v[182:183]
	v_or_b32_e32 v220, 48, v142
	v_lshl_add_u64 v[182:183], v[184:185], 0, v[182:183]
	v_ashrrev_i32_e32 v221, 31, v220
	v_add_u32_e32 v202, 0xffff8030, v142
	v_cmp_gt_i32_e32 vcc, s40, v220
	v_lshl_add_u64 v[194:195], v[182:183], 0, v[140:141]
	global_load_dwordx4 v[182:185], v[194:195], off nt
	global_load_dwordx4 v[186:189], v[194:195], off offset:64 nt
	global_load_dwordx4 v[190:193], v[194:195], off offset:512 nt
	s_nop 0
	global_load_dwordx4 v[194:197], v[194:195], off offset:576 nt
	v_cndmask_b32_e32 v203, 0, v221, vcc
	v_cndmask_b32_e32 v202, v202, v220, vcc
	v_cndmask_b32_e32 v205, v201, v224, vcc
	v_cndmask_b32_e32 v204, v225, v226, vcc
	v_lshlrev_b64 v[202:203], 12, v[202:203]
	v_lshl_add_u64 v[202:203], v[204:205], 0, v[202:203]
	v_lshl_add_u64 v[214:215], v[202:203], 0, v[140:141]
	global_load_dwordx4 v[202:205], v[214:215], off nt
	global_load_dwordx4 v[206:209], v[214:215], off offset:64 nt
	global_load_dwordx4 v[210:213], v[214:215], off offset:512 nt
	s_nop 0
	global_load_dwordx4 v[214:217], v[214:215], off offset:576 nt
	v_lshlrev_b64 v[222:223], 12, v[142:143]
	v_lshlrev_b64 v[198:199], 12, v[198:199]
	v_lshl_add_u64 v[222:223], s[90:91], 0, v[222:223]
	v_lshl_add_u64 v[198:199], s[90:91], 0, v[198:199]
	v_lshl_add_u64 v[222:223], v[222:223], 0, v[140:141]
	v_lshl_add_u64 v[198:199], v[198:199], 0, v[140:141]
	v_cmp_gt_i32_e32 vcc, s44, v142
	s_waitcnt vmcnt(0)
	v_pk_add_f32 v[126:127], v[126:127], v[152:153]
	v_pk_add_f32 v[124:125], v[124:125], v[150:151]
	v_pk_add_f32 v[122:123], v[122:123], v[156:157]
	v_pk_add_f32 v[120:121], v[120:121], v[154:155]
	v_pk_add_f32 v[94:95], v[94:95], v[180:181]
	v_pk_add_f32 v[92:93], v[92:93], v[178:179]
	v_pk_add_f32 v[114:115], v[114:115], v[160:161]
	v_pk_add_f32 v[112:113], v[112:113], v[158:159]
	v_pk_add_f32 v[106:107], v[106:107], v[164:165]
	v_pk_add_f32 v[104:105], v[104:105], v[162:163]
	global_store_dwordx4 v[222:223], v[124:127], off
	global_store_dwordx4 v[222:223], v[120:123], off offset:64
	global_store_dwordx4 v[222:223], v[112:115], off offset:512
	global_store_dwordx4 v[222:223], v[104:107], off offset:576
	global_store_dwordx4 v[198:199], v[92:95], off offset:576
	v_pk_add_f32 v[102:103], v[102:103], v[176:177]
	v_pk_add_f32 v[100:101], v[100:101], v[174:175]
	v_lshlrev_b64 v[92:93], 12, v[218:219]
	v_lshl_add_u64 v[92:93], s[90:91], 0, v[92:93]
	global_store_dwordx4 v[198:199], v[100:103], off offset:512
	v_pk_add_f32 v[78:79], v[78:79], v[196:197]
	v_pk_add_f32 v[76:77], v[76:77], v[194:195]
	v_lshl_add_u64 v[100:101], v[92:93], 0, v[140:141]
	global_store_dwordx4 v[100:101], v[76:79], off offset:576
	v_pk_add_f32 v[86:87], v[86:87], v[192:193]
	v_pk_add_f32 v[84:85], v[84:85], v[190:191]
	v_lshlrev_b64 v[76:77], 12, v[220:221]
	v_lshl_add_u64 v[76:77], s[90:91], 0, v[76:77]
	global_store_dwordx4 v[100:101], v[84:87], off offset:512
	v_pk_add_f32 v[66:67], v[66:67], v[216:217]
	v_pk_add_f32 v[64:65], v[64:65], v[214:215]
	v_lshl_add_u64 v[84:85], v[76:77], 0, v[140:141]
	v_add_u32_e32 v150, 0x80, v142
	global_store_dwordx4 v[84:85], v[64:67], off offset:576
	v_ashrrev_i32_e32 v151, 31, v150
	v_add_u32_e32 v152, 0x90, v142
	v_add_u32_e32 v64, 0xffff8080, v142
	v_cndmask_b32_e32 v65, 0, v151, vcc
	v_cndmask_b32_e32 v64, v64, v150, vcc
	v_cndmask_b32_e32 v67, v201, v224, vcc
	v_cndmask_b32_e32 v66, v225, v226, vcc
	v_lshlrev_b64 v[64:65], 12, v[64:65]
	v_pk_add_f32 v[106:107], v[118:119], v[168:169]
	v_pk_add_f32 v[104:105], v[116:117], v[166:167]
	v_pk_add_f32 v[110:111], v[110:111], v[172:173]
	v_pk_add_f32 v[108:109], v[108:109], v[170:171]
	v_pk_add_f32 v[94:95], v[98:99], v[184:185]
	v_pk_add_f32 v[92:93], v[96:97], v[182:183]
; __device__ __forceinline__ unsigned cvt_pk_bf16(float lo, float hi) { f32x2 f = {lo, hi}; bf16x2_t v = __builtin_convertvector(f, bf16x2_t); return __builtin_bit_cast(unsigned, v); }
;     __device__ __forceinline__ void operator()(const f32x4 (&acc)[2][2][4][2], const Unit& u, int wr, int wc, int fr, int fq) const {
;     ...
;         for (int ai = 0; ai < 2; ++ai) {
;             f32x4 rr[4][2][2];
; #pragma unroll
;             for (int m = 0; m < 4; ++m) {
;                 const int row = row0 + ai * 128 + m * 16;
;                 const float* rrow = (row < NTOKP ? rp + (size_t)row * D : rs + (size_t)(row - NTOKP) * D) + col0;
; #pragma unroll
;                 for (int bj = 0; bj < 2; ++bj)
; #pragma unroll
;                     for (int n = 0; n < 2; ++n) rr[m][bj][n] = *(const f32x4*)(rrow + bj * 128 + n * 16);
;             }
; #pragma unroll
;             for (int m = 0; m < 4; ++m) {
;                 const int row = row0 + ai * 128 + m * 16; float* orow = out + (size_t)row * D + col0; float ss = 0.f;
; #pragma unroll
;                 for (int bj = 0; bj < 2; ++bj)
; #pragma unroll
;                     for (int n = 0; n < 2; ++n) {
;                         const f32x4 x = rr[m][bj][n] + acc[ai][bj][m][n];
;                         *(f32x4*)(orow + bj * 128 + n * 16) = x; ss += (x[0] * x[0] + x[1] * x[1]) + (x[2] * x[2] + x[3] * x[3]);
;                         if (xb) { u32x2 w; w.x = cvt_pk_bf16(x[0], x[1]); w.y = cvt_pk_bf16(x[2], x[3]); *(u32x2*)(xb + (size_t)row * D + col0 + bj * 128 + n * 16) = w; }
;                     }
;                 if (ssq) { ss += __shfl_xor(ss, 16); ss += __shfl_xor(ss, 32); if (fq == 0) ssq[row * 16 + u.pn * 4 + wc] = ss; }
;             }
	v_pk_add_f32 v[90:91], v[90:91], v[188:189]
	v_pk_add_f32 v[88:89], v[88:89], v[186:187]
	v_pk_add_f32 v[78:79], v[82:83], v[204:205]
	v_pk_add_f32 v[76:77], v[80:81], v[202:203]
	v_pk_add_f32 v[74:75], v[74:75], v[208:209]
	v_pk_add_f32 v[72:73], v[72:73], v[206:207]
	v_pk_add_f32 v[70:71], v[70:71], v[212:213]
	v_pk_add_f32 v[68:69], v[68:69], v[210:211]
	v_lshl_add_u64 v[64:65], v[66:67], 0, v[64:65]
	v_ashrrev_i32_e32 v153, 31, v152
	v_add_u32_e32 v80, 0xffff8090, v142
	v_cmp_gt_i32_e32 vcc, s45, v142
	global_store_dwordx4 v[198:199], v[104:107], off
	global_store_dwordx4 v[198:199], v[108:111], off offset:64
	global_store_dwordx4 v[100:101], v[92:95], off
	global_store_dwordx4 v[100:101], v[88:91], off offset:64
	global_store_dwordx4 v[84:85], v[76:79], off
	global_store_dwordx4 v[84:85], v[72:75], off offset:64
	global_store_dwordx4 v[84:85], v[68:71], off offset:512
	v_lshl_add_u64 v[76:77], v[64:65], 0, v[140:141]
	v_cndmask_b32_e32 v81, 0, v153, vcc
	v_cndmask_b32_e32 v80, v80, v152, vcc
	global_load_dwordx4 v[64:67], v[76:77], off nt
	global_load_dwordx4 v[68:71], v[76:77], off offset:64 nt
	global_load_dwordx4 v[72:75], v[76:77], off offset:512 nt
	s_nop 0
	global_load_dwordx4 v[76:79], v[76:77], off offset:576 nt
	v_cndmask_b32_e32 v83, v201, v224, vcc
	v_cndmask_b32_e32 v82, v225, v226, vcc
	v_lshlrev_b64 v[80:81], 12, v[80:81]
	v_add_u32_e32 v154, 0xa0, v142
	v_lshl_add_u64 v[80:81], v[82:83], 0, v[80:81]
	v_ashrrev_i32_e32 v155, 31, v154
	v_add_u32_e32 v96, 0xffff80a0, v142
	v_cmp_gt_i32_e32 vcc, s46, v142
	v_lshl_add_u64 v[92:93], v[80:81], 0, v[140:141]
	global_load_dwordx4 v[80:83], v[92:93], off nt
	global_load_dwordx4 v[84:87], v[92:93], off offset:64 nt
	global_load_dwordx4 v[88:91], v[92:93], off offset:512 nt
	s_nop 0
	global_load_dwordx4 v[92:95], v[92:93], off offset:576 nt
	v_cndmask_b32_e32 v97, 0, v155, vcc
	v_cndmask_b32_e32 v96, v96, v154, vcc
	v_cndmask_b32_e32 v99, v201, v224, vcc
	v_cndmask_b32_e32 v98, v225, v226, vcc
	v_lshlrev_b64 v[96:97], 12, v[96:97]
	v_add_u32_e32 v156, 0xb0, v142
	v_lshl_add_u64 v[96:97], v[98:99], 0, v[96:97]
	v_ashrrev_i32_e32 v157, 31, v156
	v_add_u32_e32 v112, 0xffff80b0, v142
	v_cmp_gt_i32_e32 vcc, s47, v142
	v_lshl_add_u64 v[108:109], v[96:97], 0, v[140:141]
	global_load_dwordx4 v[96:99], v[108:109], off nt
	global_load_dwordx4 v[100:103], v[108:109], off offset:64 nt
	global_load_dwordx4 v[104:107], v[108:109], off offset:512 nt
	s_nop 0
	global_load_dwordx4 v[108:111], v[108:109], off offset:576 nt
	v_cndmask_b32_e32 v113, 0, v157, vcc
	v_cndmask_b32_e32 v112, v112, v156, vcc
	v_cndmask_b32_e32 v115, v201, v224, vcc
	v_cndmask_b32_e32 v114, v225, v226, vcc
	v_lshlrev_b64 v[112:113], 12, v[112:113]
	v_lshl_add_u64 v[112:113], v[114:115], 0, v[112:113]
	v_lshl_add_u64 v[124:125], v[112:113], 0, v[140:141]
	global_load_dwordx4 v[112:115], v[124:125], off nt
	global_load_dwordx4 v[116:119], v[124:125], off offset:64 nt
	global_load_dwordx4 v[120:123], v[124:125], off offset:512 nt
	s_nop 0
	global_load_dwordx4 v[124:127], v[124:125], off offset:576 nt
	v_lshlrev_b64 v[142:143], 12, v[150:151]
	v_lshl_add_u64 v[142:143], s[90:91], 0, v[142:143]
	v_lshl_add_u64 v[142:143], v[142:143], 0, v[140:141]
	s_and_b64 vcc, exec, s[4:5]
	s_mov_b64 s[4:5], -1
	s_waitcnt vmcnt(15)
	v_pk_add_f32 v[62:63], v[62:63], v[66:67]
	v_pk_add_f32 v[60:61], v[60:61], v[64:65]
	s_waitcnt vmcnt(13)
	v_pk_add_f32 v[54:55], v[54:55], v[74:75]
	s_waitcnt vmcnt(12)
	v_pk_add_f32 v[46:47], v[46:47], v[78:79]
	v_pk_add_f32 v[44:45], v[44:45], v[76:77]
	global_store_dwordx4 v[142:143], v[44:47], off offset:576
	v_pk_add_f32 v[52:53], v[52:53], v[72:73]
	global_store_dwordx4 v[142:143], v[52:55], off offset:512
	v_lshlrev_b64 v[44:45], 12, v[152:153]
	v_lshl_add_u64 v[44:45], s[90:91], 0, v[44:45]
	v_lshl_add_u64 v[52:53], v[44:45], 0, v[140:141]
	v_pk_add_f32 v[58:59], v[58:59], v[70:71]
	s_waitcnt vmcnt(11)
	v_pk_add_f32 v[38:39], v[38:39], v[90:91]
	s_waitcnt vmcnt(10)
	v_pk_add_f32 v[30:31], v[30:31], v[94:95]
	v_pk_add_f32 v[28:29], v[28:29], v[92:93]
	global_store_dwordx4 v[52:53], v[28:31], off offset:576
	v_pk_add_f32 v[36:37], v[36:37], v[88:89]
	global_store_dwordx4 v[52:53], v[36:39], off offset:512
	v_lshlrev_b64 v[28:29], 12, v[154:155]
	v_lshl_add_u64 v[28:29], s[90:91], 0, v[28:29]
	v_lshl_add_u64 v[36:37], v[28:29], 0, v[140:141]
	v_pk_add_f32 v[56:57], v[56:57], v[68:69]
	v_pk_add_f32 v[46:47], v[50:51], v[82:83]
	v_pk_add_f32 v[44:45], v[48:49], v[80:81]
	s_waitcnt vmcnt(9)
	v_pk_add_f32 v[22:23], v[22:23], v[106:107]
	s_waitcnt vmcnt(8)
	v_pk_add_f32 v[14:15], v[14:15], v[110:111]
	v_pk_add_f32 v[12:13], v[12:13], v[108:109]
	global_store_dwordx4 v[36:37], v[12:15], off offset:576
	v_pk_add_f32 v[20:21], v[20:21], v[104:105]
	v_pk_add_f32 v[42:43], v[42:43], v[86:87]
	v_lshlrev_b64 v[12:13], 12, v[156:157]
	v_lshl_add_u64 v[12:13], s[90:91], 0, v[12:13]
	v_pk_add_f32 v[40:41], v[40:41], v[84:85]
	v_pk_add_f32 v[30:31], v[34:35], v[98:99]
	v_pk_add_f32 v[28:29], v[32:33], v[96:97]
	v_pk_add_f32 v[26:27], v[26:27], v[102:103]
	v_pk_add_f32 v[24:25], v[24:25], v[100:101]
	global_store_dwordx4 v[36:37], v[20:23], off offset:512
	s_waitcnt vmcnt(9)
	v_pk_add_f32 v[14:15], v[18:19], v[114:115]
	s_waitcnt vmcnt(8)
	v_pk_add_f32 v[10:11], v[10:11], v[118:119]
	v_lshl_add_u64 v[20:21], v[12:13], 0, v[140:141]
	v_pk_add_f32 v[12:13], v[16:17], v[112:113]
	v_pk_add_f32 v[8:9], v[8:9], v[116:117]
	s_waitcnt vmcnt(7)
	v_pk_add_f32 v[6:7], v[6:7], v[122:123]
	v_pk_add_f32 v[4:5], v[4:5], v[120:121]
	s_waitcnt vmcnt(6)
	v_pk_add_f32 v[2:3], v[2:3], v[126:127]
	v_pk_add_f32 v[0:1], v[0:1], v[124:125]
	global_store_dwordx4 v[142:143], v[60:63], off
	global_store_dwordx4 v[142:143], v[56:59], off offset:64
	global_store_dwordx4 v[52:53], v[44:47], off
	global_store_dwordx4 v[52:53], v[40:43], off offset:64
	global_store_dwordx4 v[36:37], v[28:31], off
	global_store_dwordx4 v[36:37], v[24:27], off offset:64
	global_store_dwordx4 v[20:21], v[12:15], off
	global_store_dwordx4 v[20:21], v[8:11], off offset:64
	global_store_dwordx4 v[20:21], v[4:7], off offset:512
	global_store_dwordx4 v[20:21], v[0:3], off offset:576
	s_cbranch_vccnz .LBB0_1360
	s_andn2_b64 vcc, exec, s[10:11]
	s_cbranch_vccnz .LBB0_1359
	s_barrier
	s_branch .LBB0_1359
